# GEMM loops: 29 LDS-DMA address computations (64-bit VALU adds) replaced by saddr-form loads
# baseline (speedup 1.0000x reference)
; #define PG8_STAGE(bufoff, gbase, voff) do { _Pragma("unroll") for (int _i = 0; _i < 2; ++_i) \
;         __builtin_amdgcn_global_load_lds((const unsigned*)((const char*)(gbase) + (voff)[_i]), (LAS unsigned*)(lds + (bufoff) + ldsw + _i * 8192), 16, 0, 0); } while (0)
; #define PG8_WAIT_V(n) asm volatile("s_waitcnt vmcnt(" #n ")" ::: "memory")
; #define PG8_BAR __builtin_amdgcn_s_barrier()
; template <class Epi>
; DI void gemm_phase(int wid0, LAS unsigned char* lds, const Gemm g, const StaticOrder& S, const Epi& E) {
;     ...
;     if (wr == 1) PG8_BAR;
;     PG8_WAIT_V(2); PG8_BAR;
;     PG8_STAGE(PG8_SB(1, 0), cB + kstep, voffB); PG8_STAGE(PG8_SA(1, 0), cA + kstep, voffA); PG8_STAGE(PG8_SB(1, 1), cB + hstep + kstep, voffB);
;     PG8_WAIT_V(6); PG8_BAR;
.LBB0_48:
	v_lshrrev_b32_e32 v18, 1, v16
	v_and_b32_e32 v18, 24, v18
	v_and_b32_e32 v17, 15, v16
	v_lshlrev_b32_e32 v19, 1, v18
	v_lshlrev_b32_e32 v16, 2, v16
	s_sext_i32_i8 s21, s2
	v_lshl_or_b32 v146, s12, 6, v17
	v_lshl_or_b32 v17, v17, 6, v19
	s_lshl_b32 s2, s12, 13
	v_and_b32_e32 v16, 32, v16
	v_bitop3_b32 v19, v17, s2, v16 bitop3:0xde
	s_lshl_b32 s2, s11, 5
	s_and_b32 s14, s2, 0x60
	s_lshl_b32 s2, s14, 7
	s_add_i32 m0, s73, 0x18000
	v_lshl_add_u64 v[8:9], v[8:9], 0, s[30:31]
	v_bitop3_b32 v147, v17, s2, v16 bitop3:0xde
	s_waitcnt vmcnt(2)
	s_barrier
	global_load_lds_dwordx4 v[8:9], off
	v_lshl_add_u64 v[6:7], v[6:7], 0, s[30:31]
	s_add_i32 m0, s73, 0x1a000
	s_add_i32 s2, s73, 0x8000
	s_add_i32 s77, s73, 0xa000
	global_load_lds_dwordx4 v[6:7], off
	v_lshl_add_u64 v[2:3], v[2:3], 0, s[30:31]
	s_mov_b32 m0, s2
	s_add_u32 s12, s68, 0x40080
	global_load_lds_dwordx4 v[2:3], off
	v_lshl_add_u64 v[2:3], v[4:5], 0, s[30:31]
	s_mov_b32 m0, s77
	s_addc_u32 s13, s69, 0
	global_load_lds_dwordx4 v[2:3], off
	s_add_i32 m0, s73, 0x1c000
	s_nop 0
	global_load_lds_dwordx4 v0, s[12:13]
	v_lshl_add_u64 v[2:3], s[12:13], 0, v[130:131]
	s_add_i32 m0, s73, 0x1e000
	s_cmpk_lt_u32 s10, 0x100
	global_load_lds_dwordx4 v[2:3], off
	v_lshlrev_b32_e32 v2, 14, v14
	v_and_b32_e32 v2, 0xffff8000, v2
	v_lshl_add_u32 v2, v13, 11, v2
	v_and_b32_e32 v3, 1, v14
	v_lshl_or_b32 v2, v3, 6, v2
	v_lshl_add_u32 v136, v15, 1, v2
	v_lshlrev_b32_e32 v2, 14, v10
	v_and_b32_e32 v2, 0xffff8000, v2
	s_waitcnt vmcnt(6)
	v_lshl_add_u32 v2, v11, 11, v2
	v_and_b32_e32 v3, 1, v10
	v_lshl_or_b32 v2, v3, 6, v2
	s_cselect_b64 s[10:11], -1, 0
	v_or_b32_e32 v148, s14, v18
	v_mov_b32_e32 v137, v1
	v_lshl_add_u32 v138, v12, 1, v2
	v_mov_b32_e32 v139, v1
	s_mov_b32 s78, 0
	v_add_u32_e32 v149, 0, v19
	s_barrier
	s_branch .LBB0_51

; #define PG8_STAGE(bufoff, gbase, voff) do { _Pragma("unroll") for (int _i = 0; _i < 2; ++_i) \
;         __builtin_amdgcn_global_load_lds((const unsigned*)((const char*)(gbase) + (voff)[_i]), (LAS unsigned*)(lds + (bufoff) + ldsw + _i * 8192), 16, 0, 0); } while (0)
; #define PG8_LDA(dst, b, h) do { _Pragma("unroll") for (int m = 0; m < 4; ++m) _Pragma("unroll") for (int k = 0; k < 2; ++k) dst[m][k] = *(const LAS bf16x8*)(lds + PG8_SA(b, h) + aoff + m * 2048 + k * 1024); } while (0)
; #define PG8_LDB(dst, b, h) do { _Pragma("unroll") for (int n = 0; n < 2; ++n) _Pragma("unroll") for (int k = 0; k < 2; ++k) dst[n][k] = *(const LAS bf16x8*)(lds + PG8_SB(b, h) + boff + n * 2048 + k * 1024); } while (0)
; #define PG8_MMA(ai, bj, At, Bt) do { __builtin_amdgcn_s_setprio(1); _Pragma("unroll") for (int m = 0; m < 4; ++m) _Pragma("unroll") for (int n = 0; n < 2; ++n) _Pragma("unroll") for (int k = 0; k < 2; ++k) \
;         acc[ai][bj][m][n] = __builtin_amdgcn_mfma_f32_16x16x32_bf16(Bt[n][k], At[m][k], acc[ai][bj][m][n], 0, 0, 0); __builtin_amdgcn_s_setprio(0); } while (0)
; #define PG8_WAIT_V(n) asm volatile("s_waitcnt vmcnt(" #n ")" ::: "memory")
; #define PG8_WAIT_L(n) asm volatile("s_waitcnt lgkmcnt(" #n ")" ::: "memory")
; #define PG8_BAR __builtin_amdgcn_s_barrier()
; #define PG8_SCHED __builtin_amdgcn_sched_barrier(0)
; template <class Epi>
; DI void gemm_phase(int wid0, LAS unsigned char* lds, const Gemm g, const StaticOrder& S, const Epi& E) {
;     ...
;             const char* a1 = cA + (size_t)(t + 1) * kstep;
;             const char* a2 = last ? nA : cA + (size_t)(t + 2) * kstep; const char* b2 = last ? nB : cB + (size_t)(t + 2) * kstep;
;             const char* a3 = a2 + kstep; const char* b3 = b2 + kstep;
;             PG8_LDB(B0, 0, 0); PG8_LDB(B1, 0, 1); PG8_SCHED; PG8_LDA(At, 0, 0); PG8_STAGE(PG8_SA(1, 1), a1 + hstep, voffA);
;             PG8_WAIT_V(8); PG8_WAIT_L(0); PG8_BAR; PG8_MMA(0, 0, At, B0); PG8_MMA(0, 1, At, B1); PG8_BAR; PG8_SCHED;
;             PG8_LDA(At, 0, 1); PG8_STAGE(PG8_SB(0, 0), b2, voffB); PG8_STAGE(PG8_SB(0, 1), b2 + hstep, voffB); PG8_STAGE(PG8_SA(0, 0), a2, voffA);
;             PG8_WAIT_V(8); PG8_WAIT_L(0); PG8_BAR; PG8_MMA(1, 0, At, B0); PG8_MMA(1, 1, At, B1); PG8_BAR; PG8_SCHED;
.LBB0_58:
	s_add_u32 s68, s22, 0xfffc0080
	s_addc_u32 s69, s23, -1
	s_add_i32 s80, 0, 0x10000
	s_cmp_eq_u32 s79, 12
	s_cselect_b32 s71, s15, s69
	s_cselect_b32 s70, s40, s68
	v_add_u32_e32 v144, s80, v147
	s_cselect_b32 s69, s13, s67
	s_cselect_b32 s68, s41, s66
	s_add_i32 s82, 0, 0x14000
	ds_read_b128 v[140:143], v144
	ds_read_b128 v[150:153], v144 offset:1024
	ds_read_b128 v[154:157], v144 offset:2048
	ds_read_b128 v[158:161], v144 offset:3072
	v_add_u32_e32 v144, s82, v147
	ds_read_b128 v[176:179], v144
	ds_read_b128 v[180:183], v144 offset:1024
	ds_read_b128 v[190:193], v144 offset:2048
	ds_read_b128 v[194:197], v144 offset:3072
	s_add_i32 m0, s73, 0xc000
	ds_read_b128 v[198:201], v149
	ds_read_b128 v[202:205], v149 offset:1024
	ds_read_b128 v[206:209], v149 offset:2048
	ds_read_b128 v[210:213], v149 offset:3072
	ds_read_b128 v[214:217], v149 offset:4096
	ds_read_b128 v[218:221], v149 offset:5120
	ds_read_b128 v[222:225], v149 offset:6144
	ds_read_b128 v[226:229], v149 offset:7168
	global_load_lds_dwordx4 v136, s[22:23]
	s_add_i32 m0, s73, 0xe000
	s_nop 0
	global_load_lds_dwordx4 v138, s[22:23]
	s_waitcnt vmcnt(8)
	s_waitcnt lgkmcnt(0)
	s_barrier
	s_setprio 1
	s_waitcnt lgkmcnt(0)
	v_mfma_f32_16x16x32_bf16 v[126:129], v[140:143], v[198:201], v[126:129]
	v_mfma_f32_16x16x32_bf16 v[122:125], v[154:157], v[198:201], v[122:125]
	v_mfma_f32_16x16x32_bf16 v[110:113], v[140:143], v[206:209], v[110:113]
	v_mfma_f32_16x16x32_bf16 v[106:109], v[154:157], v[206:209], v[106:109]
	v_mfma_f32_16x16x32_bf16 v[94:97], v[140:143], v[214:217], v[94:97]
	v_mfma_f32_16x16x32_bf16 v[90:93], v[154:157], v[214:217], v[90:93]
	v_mfma_f32_16x16x32_bf16 v[78:81], v[140:143], v[222:225], v[78:81]
	v_mfma_f32_16x16x32_bf16 v[74:77], v[154:157], v[222:225], v[74:77]
	v_mfma_f32_16x16x32_bf16 v[126:129], v[150:153], v[202:205], v[126:129]
	v_mfma_f32_16x16x32_bf16 v[122:125], v[158:161], v[202:205], v[122:125]
	v_mfma_f32_16x16x32_bf16 v[110:113], v[150:153], v[210:213], v[110:113]
	v_mfma_f32_16x16x32_bf16 v[106:109], v[158:161], v[210:213], v[106:109]
	v_mfma_f32_16x16x32_bf16 v[94:97], v[150:153], v[218:221], v[94:97]
	v_mfma_f32_16x16x32_bf16 v[90:93], v[158:161], v[218:221], v[90:93]
	v_mfma_f32_16x16x32_bf16 v[78:81], v[150:153], v[226:229], v[78:81]
	v_mfma_f32_16x16x32_bf16 v[74:77], v[158:161], v[226:229], v[74:77]
	s_setprio 0
	s_setprio 1
	v_mfma_f32_16x16x32_bf16 v[118:121], v[176:179], v[198:201], v[118:121]
	v_mfma_f32_16x16x32_bf16 v[114:117], v[190:193], v[198:201], v[114:117]
	v_mfma_f32_16x16x32_bf16 v[102:105], v[176:179], v[206:209], v[102:105]
	v_mfma_f32_16x16x32_bf16 v[98:101], v[190:193], v[206:209], v[98:101]
	v_mfma_f32_16x16x32_bf16 v[86:89], v[176:179], v[214:217], v[86:89]
	v_mfma_f32_16x16x32_bf16 v[82:85], v[190:193], v[214:217], v[82:85]
	v_mfma_f32_16x16x32_bf16 v[70:73], v[176:179], v[222:225], v[70:73]
	v_mfma_f32_16x16x32_bf16 v[66:69], v[190:193], v[222:225], v[66:69]
	v_mfma_f32_16x16x32_bf16 v[118:121], v[180:183], v[202:205], v[118:121]
	v_mfma_f32_16x16x32_bf16 v[114:117], v[194:197], v[202:205], v[114:117]
	v_mfma_f32_16x16x32_bf16 v[102:105], v[180:183], v[210:213], v[102:105]
	v_mfma_f32_16x16x32_bf16 v[98:101], v[194:197], v[210:213], v[98:101]
	v_mfma_f32_16x16x32_bf16 v[86:89], v[180:183], v[218:221], v[86:89]
	v_mfma_f32_16x16x32_bf16 v[82:85], v[194:197], v[218:221], v[82:85]
	v_mfma_f32_16x16x32_bf16 v[70:73], v[180:183], v[226:229], v[70:73]
	v_mfma_f32_16x16x32_bf16 v[66:69], v[194:197], v[226:229], v[66:69]
	s_setprio 0
	s_barrier
	s_add_i32 s80, s80, s72
	v_lshl_add_u64 v[144:145], s[68:69], 0, v[0:1]
	s_mov_b32 m0, s80
	ds_read_b128 v[198:201], v149 offset:16384
	ds_read_b128 v[202:205], v149 offset:17408
	ds_read_b128 v[206:209], v149 offset:18432
	ds_read_b128 v[210:213], v149 offset:19456
	ds_read_b128 v[214:217], v149 offset:20480
	ds_read_b128 v[218:221], v149 offset:21504
	ds_read_b128 v[222:225], v149 offset:22528
	ds_read_b128 v[226:229], v149 offset:23552
	global_load_lds_dwordx4 v[144:145], off
	s_add_i32 m0, s80, 0x2000
	s_add_u32 s80, s68, 0x40000
	v_lshl_add_u64 v[162:163], s[68:69], 0, v[130:131]
	s_addc_u32 s81, s69, 0
	s_add_i32 s82, s82, s72
	global_load_lds_dwordx4 v[162:163], off
	s_mov_b32 m0, s82
	v_lshl_add_u64 v[236:237], s[70:71], 0, v[132:133]
	global_load_lds_dwordx4 v0, s[80:81]
	s_add_i32 m0, s82, 0x2000
	s_nop 0
	global_load_lds_dwordx4 v130, s[80:81]
	v_lshl_add_u64 v[230:231], s[70:71], 0, v[134:135]
	s_mov_b32 m0, s73
	s_nop 0
	global_load_lds_dwordx4 v[230:231], off
	s_mov_b32 m0, s74
	s_nop 0
	global_load_lds_dwordx4 v[236:237], off
	s_waitcnt vmcnt(8)
	s_waitcnt lgkmcnt(0)
	s_barrier
; #define PG8_STAGE(bufoff, gbase, voff) do { _Pragma("unroll") for (int _i = 0; _i < 2; ++_i) \
;         __builtin_amdgcn_global_load_lds((const unsigned*)((const char*)(gbase) + (voff)[_i]), (LAS unsigned*)(lds + (bufoff) + ldsw + _i * 8192), 16, 0, 0); } while (0)
; #define PG8_LDA(dst, b, h) do { _Pragma("unroll") for (int m = 0; m < 4; ++m) _Pragma("unroll") for (int k = 0; k < 2; ++k) dst[m][k] = *(const LAS bf16x8*)(lds + PG8_SA(b, h) + aoff + m * 2048 + k * 1024); } while (0)
; #define PG8_LDB(dst, b, h) do { _Pragma("unroll") for (int n = 0; n < 2; ++n) _Pragma("unroll") for (int k = 0; k < 2; ++k) dst[n][k] = *(const LAS bf16x8*)(lds + PG8_SB(b, h) + boff + n * 2048 + k * 1024); } while (0)
; #define PG8_MMA(ai, bj, At, Bt) do { __builtin_amdgcn_s_setprio(1); _Pragma("unroll") for (int m = 0; m < 4; ++m) _Pragma("unroll") for (int n = 0; n < 2; ++n) _Pragma("unroll") for (int k = 0; k < 2; ++k) \
;         acc[ai][bj][m][n] = __builtin_amdgcn_mfma_f32_16x16x32_bf16(Bt[n][k], At[m][k], acc[ai][bj][m][n], 0, 0, 0); __builtin_amdgcn_s_setprio(0); } while (0)
; #define PG8_WAIT_V(n) asm volatile("s_waitcnt vmcnt(" #n ")" ::: "memory")
; #define PG8_WAIT_L(n) asm volatile("s_waitcnt lgkmcnt(" #n ")" ::: "memory")
; #define PG8_BAR __builtin_amdgcn_s_barrier()
; #define PG8_SCHED __builtin_amdgcn_sched_barrier(0)
; template <class Epi>
; DI void gemm_phase(int wid0, LAS unsigned char* lds, const Gemm g, const StaticOrder& S, const Epi& E) {
;     ...
;             PG8_WAIT_V(8); PG8_WAIT_L(0); PG8_BAR; PG8_MMA(1, 0, At, B0); PG8_MMA(1, 1, At, B1); PG8_BAR; PG8_SCHED;
;             PG8_LDB(B0, 1, 0); PG8_LDB(B1, 1, 1); PG8_SCHED; PG8_LDA(At, 1, 0); PG8_STAGE(PG8_SA(0, 1), a2 + hstep, voffA);
;             PG8_WAIT_V(8); PG8_WAIT_L(0); PG8_BAR; PG8_MMA(0, 0, At, B0); PG8_MMA(0, 1, At, B1); PG8_BAR; PG8_SCHED;
	s_setprio 1
	s_waitcnt lgkmcnt(0)
	v_mfma_f32_16x16x32_bf16 v[62:65], v[140:143], v[198:201], v[62:65]
	v_mfma_f32_16x16x32_bf16 v[58:61], v[154:157], v[198:201], v[58:61]
	v_mfma_f32_16x16x32_bf16 v[46:49], v[140:143], v[206:209], v[46:49]
	v_mfma_f32_16x16x32_bf16 v[42:45], v[154:157], v[206:209], v[42:45]
	v_mfma_f32_16x16x32_bf16 v[30:33], v[140:143], v[214:217], v[30:33]
	v_mfma_f32_16x16x32_bf16 v[26:29], v[154:157], v[214:217], v[26:29]
	v_mfma_f32_16x16x32_bf16 v[14:17], v[140:143], v[222:225], v[14:17]
	v_mfma_f32_16x16x32_bf16 v[10:13], v[154:157], v[222:225], v[10:13]
	v_mfma_f32_16x16x32_bf16 v[62:65], v[150:153], v[202:205], v[62:65]
	v_mfma_f32_16x16x32_bf16 v[58:61], v[158:161], v[202:205], v[58:61]
	v_mfma_f32_16x16x32_bf16 v[46:49], v[150:153], v[210:213], v[46:49]
	v_mfma_f32_16x16x32_bf16 v[42:45], v[158:161], v[210:213], v[42:45]
	v_mfma_f32_16x16x32_bf16 v[30:33], v[150:153], v[218:221], v[30:33]
	v_mfma_f32_16x16x32_bf16 v[26:29], v[158:161], v[218:221], v[26:29]
	v_mfma_f32_16x16x32_bf16 v[14:17], v[150:153], v[226:229], v[14:17]
	v_mfma_f32_16x16x32_bf16 v[10:13], v[158:161], v[226:229], v[10:13]
	s_setprio 0
	s_setprio 1
	v_mfma_f32_16x16x32_bf16 v[54:57], v[176:179], v[198:201], v[54:57]
	v_mfma_f32_16x16x32_bf16 v[50:53], v[190:193], v[198:201], v[50:53]
	v_mfma_f32_16x16x32_bf16 v[38:41], v[176:179], v[206:209], v[38:41]
	v_mfma_f32_16x16x32_bf16 v[34:37], v[190:193], v[206:209], v[34:37]
	v_mfma_f32_16x16x32_bf16 v[22:25], v[176:179], v[214:217], v[22:25]
	v_mfma_f32_16x16x32_bf16 v[18:21], v[190:193], v[214:217], v[18:21]
	v_mfma_f32_16x16x32_bf16 v[6:9], v[176:179], v[222:225], v[6:9]
	v_mfma_f32_16x16x32_bf16 v[2:5], v[190:193], v[222:225], v[2:5]
	v_mfma_f32_16x16x32_bf16 v[54:57], v[180:183], v[202:205], v[54:57]
	v_mfma_f32_16x16x32_bf16 v[50:53], v[194:197], v[202:205], v[50:53]
	v_mfma_f32_16x16x32_bf16 v[38:41], v[180:183], v[210:213], v[38:41]
	v_mfma_f32_16x16x32_bf16 v[34:37], v[194:197], v[210:213], v[34:37]
	v_mfma_f32_16x16x32_bf16 v[22:25], v[180:183], v[218:221], v[22:25]
	v_mfma_f32_16x16x32_bf16 v[18:21], v[194:197], v[218:221], v[18:21]
	v_mfma_f32_16x16x32_bf16 v[6:9], v[180:183], v[226:229], v[6:9]
	v_mfma_f32_16x16x32_bf16 v[2:5], v[194:197], v[226:229], v[2:5]
	s_setprio 0
	s_barrier
	s_add_i32 s80, 0, 0x18000
	s_add_i32 s81, 0, 0x1c000
	v_add_u32_e32 v158, s80, v147
	v_add_u32_e32 v189, s81, v147
	ds_read_b128 v[140:143], v158
	ds_read_b128 v[150:153], v158 offset:1024
	ds_read_b128 v[154:157], v158 offset:2048
	ds_read_b128 v[158:161], v158 offset:3072
	ds_read_b128 v[176:179], v189
	ds_read_b128 v[180:183], v189 offset:1024
	ds_read_b128 v[190:193], v189 offset:2048
	ds_read_b128 v[194:197], v189 offset:3072
	s_add_u32 s70, s70, 0x40000
	s_addc_u32 s71, s71, 0
	s_mov_b32 m0, s75
	ds_read_b128 v[198:201], v149 offset:32768
	ds_read_b128 v[202:205], v149 offset:33792
	ds_read_b128 v[206:209], v149 offset:34816
	ds_read_b128 v[210:213], v149 offset:35840
	ds_read_b128 v[214:217], v149 offset:36864
	ds_read_b128 v[218:221], v149 offset:37888
	ds_read_b128 v[222:225], v149 offset:38912
	ds_read_b128 v[226:229], v149 offset:39936
	global_load_lds_dwordx4 v134, s[70:71]
	v_lshl_add_u64 v[238:239], s[70:71], 0, v[132:133]
	s_mov_b32 m0, s76
	s_nop 0
	global_load_lds_dwordx4 v[238:239], off
	s_waitcnt vmcnt(8)
	s_waitcnt lgkmcnt(0)
	s_barrier
	s_setprio 1
	s_waitcnt lgkmcnt(0)
	v_mfma_f32_16x16x32_bf16 v[126:129], v[140:143], v[198:201], v[126:129]
	v_mfma_f32_16x16x32_bf16 v[122:125], v[154:157], v[198:201], v[122:125]
	v_mfma_f32_16x16x32_bf16 v[110:113], v[140:143], v[206:209], v[110:113]
	v_mfma_f32_16x16x32_bf16 v[106:109], v[154:157], v[206:209], v[106:109]
	v_mfma_f32_16x16x32_bf16 v[94:97], v[140:143], v[214:217], v[94:97]
	v_mfma_f32_16x16x32_bf16 v[90:93], v[154:157], v[214:217], v[90:93]
	v_mfma_f32_16x16x32_bf16 v[78:81], v[140:143], v[222:225], v[78:81]
	v_mfma_f32_16x16x32_bf16 v[74:77], v[154:157], v[222:225], v[74:77]
	v_mfma_f32_16x16x32_bf16 v[126:129], v[150:153], v[202:205], v[126:129]
	v_mfma_f32_16x16x32_bf16 v[122:125], v[158:161], v[202:205], v[122:125]
	v_mfma_f32_16x16x32_bf16 v[110:113], v[150:153], v[210:213], v[110:113]
	v_mfma_f32_16x16x32_bf16 v[106:109], v[158:161], v[210:213], v[106:109]
	v_mfma_f32_16x16x32_bf16 v[94:97], v[150:153], v[218:221], v[94:97]
	v_mfma_f32_16x16x32_bf16 v[90:93], v[158:161], v[218:221], v[90:93]
	v_mfma_f32_16x16x32_bf16 v[78:81], v[150:153], v[226:229], v[78:81]
	v_mfma_f32_16x16x32_bf16 v[74:77], v[158:161], v[226:229], v[74:77]
	s_setprio 0
	s_setprio 1
	v_mfma_f32_16x16x32_bf16 v[118:121], v[176:179], v[198:201], v[118:121]
	v_mfma_f32_16x16x32_bf16 v[114:117], v[190:193], v[198:201], v[114:117]
	v_mfma_f32_16x16x32_bf16 v[102:105], v[176:179], v[206:209], v[102:105]
	v_mfma_f32_16x16x32_bf16 v[98:101], v[190:193], v[206:209], v[98:101]
	v_mfma_f32_16x16x32_bf16 v[86:89], v[176:179], v[214:217], v[86:89]
	v_mfma_f32_16x16x32_bf16 v[82:85], v[190:193], v[214:217], v[82:85]
	v_mfma_f32_16x16x32_bf16 v[70:73], v[176:179], v[222:225], v[70:73]
	v_mfma_f32_16x16x32_bf16 v[66:69], v[190:193], v[222:225], v[66:69]
	v_mfma_f32_16x16x32_bf16 v[118:121], v[180:183], v[202:205], v[118:121]
	v_mfma_f32_16x16x32_bf16 v[114:117], v[194:197], v[202:205], v[114:117]
	v_mfma_f32_16x16x32_bf16 v[102:105], v[180:183], v[210:213], v[102:105]
	v_mfma_f32_16x16x32_bf16 v[98:101], v[194:197], v[210:213], v[98:101]
	v_mfma_f32_16x16x32_bf16 v[86:89], v[180:183], v[218:221], v[86:89]
	v_mfma_f32_16x16x32_bf16 v[82:85], v[194:197], v[218:221], v[82:85]
	v_mfma_f32_16x16x32_bf16 v[70:73], v[180:183], v[226:229], v[70:73]
	v_mfma_f32_16x16x32_bf16 v[66:69], v[194:197], v[226:229], v[66:69]
	s_setprio 0
	s_barrier
; #define PG8_STAGE(bufoff, gbase, voff) do { _Pragma("unroll") for (int _i = 0; _i < 2; ++_i) \
;         __builtin_amdgcn_global_load_lds((const unsigned*)((const char*)(gbase) + (voff)[_i]), (LAS unsigned*)(lds + (bufoff) + ldsw + _i * 8192), 16, 0, 0); } while (0)
; #define PG8_LDA(dst, b, h) do { _Pragma("unroll") for (int m = 0; m < 4; ++m) _Pragma("unroll") for (int k = 0; k < 2; ++k) dst[m][k] = *(const LAS bf16x8*)(lds + PG8_SA(b, h) + aoff + m * 2048 + k * 1024); } while (0)
; #define PG8_MMA(ai, bj, At, Bt) do { __builtin_amdgcn_s_setprio(1); _Pragma("unroll") for (int m = 0; m < 4; ++m) _Pragma("unroll") for (int n = 0; n < 2; ++n) _Pragma("unroll") for (int k = 0; k < 2; ++k) \
;         acc[ai][bj][m][n] = __builtin_amdgcn_mfma_f32_16x16x32_bf16(Bt[n][k], At[m][k], acc[ai][bj][m][n], 0, 0, 0); __builtin_amdgcn_s_setprio(0); } while (0)
; #define PG8_WAIT_V(n) asm volatile("s_waitcnt vmcnt(" #n ")" ::: "memory")
; #define PG8_WAIT_L(n) asm volatile("s_waitcnt lgkmcnt(" #n ")" ::: "memory")
; #define PG8_BAR __builtin_amdgcn_s_barrier()
; #define PG8_SCHED __builtin_amdgcn_sched_barrier(0)
; template <class Epi>
; DI void gemm_phase(int wid0, LAS unsigned char* lds, const Gemm g, const StaticOrder& S, const Epi& E) {
;     ...
;         for (int t = 0; t < nt; t += 2) {
;             const bool last = (t == nt - 2);
;             const char* a1 = cA + (size_t)(t + 1) * kstep;
;             const char* a2 = last ? nA : cA + (size_t)(t + 2) * kstep; const char* b2 = last ? nB : cB + (size_t)(t + 2) * kstep;
;     ...
;             PG8_LDA(At, 1, 1); PG8_STAGE(PG8_SB(1, 0), b3, voffB); PG8_STAGE(PG8_SB(1, 1), b3 + hstep, voffB); PG8_STAGE(PG8_SA(1, 0), a3, voffA);
;             PG8_WAIT_V(8); PG8_WAIT_L(0); PG8_BAR; PG8_MMA(1, 0, At, B0); PG8_MMA(1, 1, At, B1); PG8_BAR; PG8_SCHED;
;         }
	s_add_i32 s70, s80, s72
	v_lshl_add_u64 v[144:145], v[144:145], 0, s[30:31]
	s_mov_b32 m0, s70
	ds_read_b128 v[198:201], v149 offset:49152
	ds_read_b128 v[202:205], v149 offset:50176
	ds_read_b128 v[206:209], v149 offset:51200
	ds_read_b128 v[210:213], v149 offset:52224
	ds_read_b128 v[214:217], v149 offset:53248
	ds_read_b128 v[218:221], v149 offset:54272
	ds_read_b128 v[222:225], v149 offset:55296
	ds_read_b128 v[226:229], v149 offset:56320
	global_load_lds_dwordx4 v[144:145], off
	s_add_i32 m0, s70, 0x2000
	s_add_u32 s68, s68, 0x40080
	v_lshl_add_u64 v[144:145], v[162:163], 0, s[30:31]
	s_addc_u32 s69, s69, 0
	s_add_i32 s70, s81, s72
	global_load_lds_dwordx4 v[144:145], off
	s_mov_b32 m0, s70
	s_nop 0
	global_load_lds_dwordx4 v0, s[68:69]
	s_add_i32 m0, s70, 0x2000
	s_nop 0
	global_load_lds_dwordx4 v130, s[68:69]
	v_lshl_add_u64 v[144:145], v[230:231], 0, s[30:31]
	s_mov_b32 m0, s2
	s_nop 0
	global_load_lds_dwordx4 v[144:145], off
	v_lshl_add_u64 v[144:145], v[236:237], 0, s[30:31]
	s_mov_b32 m0, s77
	s_nop 0
	global_load_lds_dwordx4 v[144:145], off
	s_waitcnt vmcnt(8)
	s_waitcnt lgkmcnt(0)
	s_barrier
	s_setprio 1
	s_waitcnt lgkmcnt(0)
	v_mfma_f32_16x16x32_bf16 v[62:65], v[140:143], v[198:201], v[62:65]
	v_mfma_f32_16x16x32_bf16 v[58:61], v[154:157], v[198:201], v[58:61]
	v_mfma_f32_16x16x32_bf16 v[46:49], v[140:143], v[206:209], v[46:49]
	v_mfma_f32_16x16x32_bf16 v[42:45], v[154:157], v[206:209], v[42:45]
	v_mfma_f32_16x16x32_bf16 v[30:33], v[140:143], v[214:217], v[30:33]
	v_mfma_f32_16x16x32_bf16 v[26:29], v[154:157], v[214:217], v[26:29]
	v_mfma_f32_16x16x32_bf16 v[14:17], v[140:143], v[222:225], v[14:17]
	v_mfma_f32_16x16x32_bf16 v[10:13], v[154:157], v[222:225], v[10:13]
	v_mfma_f32_16x16x32_bf16 v[62:65], v[150:153], v[202:205], v[62:65]
	v_mfma_f32_16x16x32_bf16 v[58:61], v[158:161], v[202:205], v[58:61]
	v_mfma_f32_16x16x32_bf16 v[46:49], v[150:153], v[210:213], v[46:49]
	v_mfma_f32_16x16x32_bf16 v[42:45], v[158:161], v[210:213], v[42:45]
	v_mfma_f32_16x16x32_bf16 v[30:33], v[150:153], v[218:221], v[30:33]
	v_mfma_f32_16x16x32_bf16 v[26:29], v[158:161], v[218:221], v[26:29]
	v_mfma_f32_16x16x32_bf16 v[14:17], v[150:153], v[226:229], v[14:17]
	v_mfma_f32_16x16x32_bf16 v[10:13], v[158:161], v[226:229], v[10:13]
	s_setprio 0
	s_setprio 1
	v_mfma_f32_16x16x32_bf16 v[54:57], v[176:179], v[198:201], v[54:57]
	v_mfma_f32_16x16x32_bf16 v[50:53], v[190:193], v[198:201], v[50:53]
	v_mfma_f32_16x16x32_bf16 v[38:41], v[176:179], v[206:209], v[38:41]
	v_mfma_f32_16x16x32_bf16 v[34:37], v[190:193], v[206:209], v[34:37]
	v_mfma_f32_16x16x32_bf16 v[22:25], v[176:179], v[214:217], v[22:25]
	v_mfma_f32_16x16x32_bf16 v[18:21], v[190:193], v[214:217], v[18:21]
	v_mfma_f32_16x16x32_bf16 v[6:9], v[176:179], v[222:225], v[6:9]
	v_mfma_f32_16x16x32_bf16 v[2:5], v[190:193], v[222:225], v[2:5]
	v_mfma_f32_16x16x32_bf16 v[54:57], v[180:183], v[202:205], v[54:57]
	v_mfma_f32_16x16x32_bf16 v[50:53], v[194:197], v[202:205], v[50:53]
	v_mfma_f32_16x16x32_bf16 v[38:41], v[180:183], v[210:213], v[38:41]
	v_mfma_f32_16x16x32_bf16 v[34:37], v[194:197], v[210:213], v[34:37]
	v_mfma_f32_16x16x32_bf16 v[22:25], v[180:183], v[218:221], v[22:25]
	v_mfma_f32_16x16x32_bf16 v[18:21], v[194:197], v[218:221], v[18:21]
	v_mfma_f32_16x16x32_bf16 v[6:9], v[180:183], v[226:229], v[6:9]
	v_mfma_f32_16x16x32_bf16 v[2:5], v[194:197], v[226:229], v[2:5]
	s_setprio 0
	s_barrier
	s_add_i32 s79, s79, 2
	s_add_u32 s22, s22, 0x100
	s_addc_u32 s23, s23, 0
	s_add_u32 s66, s66, 0x100
	s_addc_u32 s67, s67, 0
	s_cmp_gt_u32 s79, 13
	s_cbranch_scc0 .LBB0_58
	s_and_b64 vcc, exec, s[10:11]
	s_movk_i32 s79, 0x3fff
	s_movk_i32 s40, 0x7fff
	v_readlane_b32 s41, v245, 48
	s_cbranch_vccz .LBB0_61
	s_barrier

; #define PG8_STAGE(bufoff, gbase, voff) do { _Pragma("unroll") for (int _i = 0; _i < 2; ++_i) \
;         __builtin_amdgcn_global_load_lds((const unsigned*)((const char*)(gbase) + (voff)[_i]), (LAS unsigned*)(lds + (bufoff) + ldsw + _i * 8192), 16, 0, 0); } while (0)
; #define PG8_WAIT_V(n) asm volatile("s_waitcnt vmcnt(" #n ")" ::: "memory")
; #define PG8_BAR __builtin_amdgcn_s_barrier()
; template <class Epi>
; DI void gemm_phase(int wid0, LAS unsigned char* lds, const Gemm g, const StaticOrder& S, const Epi& E) {
;     ...
;     for (int i = 0; i < 2; ++i) { int R, C; stage_rc(tid * 16 + i * 8192, R, C); const int Rb = (R & ~31) + perm32(R & 31); voffA[i] = (unsigned)(R * K + C) * 2u; voffB[i] = (unsigned)(Rb * K + C) * 2u; }
;     const size_t kstep = (size_t)(BK * 2);
;     const size_t hstep = (size_t)HALF * K * 2;
;     const size_t tstep = 2 * hstep;
;     const unsigned ldsw = (unsigned)wid * 1024u;
;     const int aoff = lds_byte(wr * 64 + fr, fq * 8), boff = lds_byte(wc * 32 + fr, fq * 8);
;     ...
;     Unit cur, nxt; int ui = 0;
;     if (!S.next(0, cur)) return;
;     f32x4 acc[2][2][4][2];
; #pragma unroll
;     for (int a = 0; a < 2; ++a)
; #pragma unroll
;         for (int b = 0; b < 2; ++b)
; #pragma unroll
;             for (int m = 0; m < 4; ++m)
; #pragma unroll
;                 for (int n = 0; n < 2; ++n) acc[a][b][m][n] = (f32x4){0.f, 0.f, 0.f, 0.f};
;     bf16x8 At[4][2], B0[2][2], B1[2][2];
;     const char* cA = (const char*)g.A + (size_t)cur.pm * tstep; const char* cB = (const char*)g.Bt + (size_t)cur.pn * tstep;
;     PG8_STAGE(PG8_SB(0, 0), cB, voffB); PG8_STAGE(PG8_SB(0, 1), cB + hstep, voffB); PG8_STAGE(PG8_SA(0, 0), cA, voffA); PG8_STAGE(PG8_SA(0, 1), cA + hstep, voffA);
;     if (wr == 1) PG8_BAR;
;     PG8_WAIT_V(2); PG8_BAR;
;     PG8_STAGE(PG8_SB(1, 0), cB + kstep, voffB); PG8_STAGE(PG8_SA(1, 0), cA + kstep, voffA); PG8_STAGE(PG8_SB(1, 1), cB + hstep + kstep, voffB);
;     PG8_WAIT_V(6); PG8_BAR;
.LBB0_133:
	v_lshrrev_b32_e32 v17, 1, v15
	v_and_b32_e32 v17, 24, v17
	v_and_b32_e32 v16, 15, v15
	v_lshlrev_b32_e32 v18, 1, v17
	v_lshlrev_b32_e32 v15, 2, v15
	s_sext_i32_i16 s68, s2
	v_lshl_or_b32 v142, s8, 6, v16
	v_lshl_or_b32 v16, v16, 6, v18
	s_lshl_b32 s2, s8, 13
	v_and_b32_e32 v15, 32, v15
	v_bitop3_b32 v18, v16, s2, v15 bitop3:0xde
	s_lshl_b32 s2, s5, 5
	s_and_b32 s5, s2, 0x60
	s_lshl_b32 s2, s5, 7
	s_add_i32 m0, s11, 0x18000
	v_lshl_add_u64 v[8:9], v[8:9], 0, s[30:31]
	v_bitop3_b32 v143, v16, s2, v15 bitop3:0xde
	s_waitcnt vmcnt(2)
	s_barrier
	global_load_lds_dwordx4 v[8:9], off
	v_lshl_add_u64 v[6:7], v[6:7], 0, s[30:31]
	s_add_i32 m0, s11, 0x1a000
	s_add_i32 s2, s11, 0x8000
	s_add_i32 s48, s11, 0xa000
	global_load_lds_dwordx4 v[6:7], off
	v_lshl_add_u64 v[2:3], v[2:3], 0, s[30:31]
	s_mov_b32 m0, s2
	s_add_u32 s8, s22, 0x40080
	global_load_lds_dwordx4 v[2:3], off
	v_lshl_add_u64 v[2:3], v[4:5], 0, s[30:31]
	s_mov_b32 m0, s48
	s_addc_u32 s9, s23, 0
	global_load_lds_dwordx4 v[2:3], off
	s_add_i32 m0, s11, 0x1c000
	s_nop 0
	global_load_lds_dwordx4 v134, s[8:9]
	v_lshl_add_u64 v[2:3], s[8:9], 0, v[130:131]
	s_add_i32 m0, s11, 0x1e000
	s_cmpk_lt_u32 s4, 0x100
	global_load_lds_dwordx4 v[2:3], off
	v_lshlrev_b32_e32 v2, 14, v13
	v_and_b32_e32 v2, 0xffff8000, v2
	v_lshl_add_u32 v2, v12, 11, v2
	v_and_b32_e32 v3, 1, v13
	v_lshl_or_b32 v2, v3, 6, v2
	v_lshl_add_u32 v138, v14, 1, v2
	v_lshlrev_b32_e32 v2, 14, v0
	v_and_b32_e32 v2, 0xffff8000, v2
	s_waitcnt vmcnt(6)
	v_lshl_add_u32 v2, v10, 11, v2
	v_and_b32_e32 v0, 1, v0
	v_lshl_or_b32 v0, v0, 6, v2
	s_cselect_b64 s[8:9], -1, 0
	v_or_b32_e32 v144, s5, v17
	v_mov_b32_e32 v139, v1
	v_lshl_add_u32 v140, v11, 1, v0
	v_mov_b32_e32 v141, v1
	s_mov_b32 s49, 0
	v_add_u32_e32 v145, 0, v18
	s_barrier
	s_branch .LBB0_136

; #define PG8_STAGE(bufoff, gbase, voff) do { _Pragma("unroll") for (int _i = 0; _i < 2; ++_i) \
;         __builtin_amdgcn_global_load_lds((const unsigned*)((const char*)(gbase) + (voff)[_i]), (LAS unsigned*)(lds + (bufoff) + ldsw + _i * 8192), 16, 0, 0); } while (0)
; #define PG8_LDA(dst, b, h) do { _Pragma("unroll") for (int m = 0; m < 4; ++m) _Pragma("unroll") for (int k = 0; k < 2; ++k) dst[m][k] = *(const LAS bf16x8*)(lds + PG8_SA(b, h) + aoff + m * 2048 + k * 1024); } while (0)
; #define PG8_LDB(dst, b, h) do { _Pragma("unroll") for (int n = 0; n < 2; ++n) _Pragma("unroll") for (int k = 0; k < 2; ++k) dst[n][k] = *(const LAS bf16x8*)(lds + PG8_SB(b, h) + boff + n * 2048 + k * 1024); } while (0)
; #define PG8_MMA(ai, bj, At, Bt) do { __builtin_amdgcn_s_setprio(1); _Pragma("unroll") for (int m = 0; m < 4; ++m) _Pragma("unroll") for (int n = 0; n < 2; ++n) _Pragma("unroll") for (int k = 0; k < 2; ++k) \
;         acc[ai][bj][m][n] = __builtin_amdgcn_mfma_f32_16x16x32_bf16(Bt[n][k], At[m][k], acc[ai][bj][m][n], 0, 0, 0); __builtin_amdgcn_s_setprio(0); } while (0)
; #define PG8_WAIT_V(n) asm volatile("s_waitcnt vmcnt(" #n ")" ::: "memory")
; #define PG8_WAIT_L(n) asm volatile("s_waitcnt lgkmcnt(" #n ")" ::: "memory")
; #define PG8_BAR __builtin_amdgcn_s_barrier()
; #define PG8_SCHED __builtin_amdgcn_sched_barrier(0)
; template <class Epi>
; DI void gemm_phase(int wid0, LAS unsigned char* lds, const Gemm g, const StaticOrder& S, const Epi& E) {
;     ...
;             const char* a1 = cA + (size_t)(t + 1) * kstep;
;             const char* a2 = last ? nA : cA + (size_t)(t + 2) * kstep; const char* b2 = last ? nB : cB + (size_t)(t + 2) * kstep;
;             const char* a3 = a2 + kstep; const char* b3 = b2 + kstep;
;             PG8_LDB(B0, 0, 0); PG8_LDB(B1, 0, 1); PG8_SCHED; PG8_LDA(At, 0, 0); PG8_STAGE(PG8_SA(1, 1), a1 + hstep, voffA);
;             PG8_WAIT_V(8); PG8_WAIT_L(0); PG8_BAR; PG8_MMA(0, 0, At, B0); PG8_MMA(0, 1, At, B1); PG8_BAR; PG8_SCHED;
;             PG8_LDA(At, 0, 1); PG8_STAGE(PG8_SB(0, 0), b2, voffB); PG8_STAGE(PG8_SB(0, 1), b2 + hstep, voffB); PG8_STAGE(PG8_SA(0, 0), a2, voffA);
;             PG8_WAIT_V(8); PG8_WAIT_L(0); PG8_BAR; PG8_MMA(1, 0, At, B0); PG8_MMA(1, 1, At, B1); PG8_BAR; PG8_SCHED;
.LBB0_139:
	s_add_u32 s22, s20, 0xfffc0080
	s_addc_u32 s23, s21, -1
	s_add_i32 s72, 0, 0x10000
	s_cmp_eq_u32 s71, 12
	s_cselect_b32 s39, s15, s23
	s_cselect_b32 s38, s66, s22
	v_add_u32_e32 v0, s72, v143
	s_cselect_b32 s23, s13, s70
	s_cselect_b32 s22, s67, s69
	s_add_i32 s74, 0, 0x14000
	ds_read_b128 v[146:149], v0
	ds_read_b128 v[150:153], v0 offset:1024
	ds_read_b128 v[154:157], v0 offset:2048
	ds_read_b128 v[158:161], v0 offset:3072
	v_add_u32_e32 v0, s74, v143
	ds_read_b128 v[176:179], v0
	ds_read_b128 v[180:183], v0 offset:1024
	ds_read_b128 v[190:193], v0 offset:2048
	ds_read_b128 v[194:197], v0 offset:3072
	s_add_i32 m0, s11, 0xc000
	ds_read_b128 v[198:201], v145
	ds_read_b128 v[202:205], v145 offset:1024
	ds_read_b128 v[206:209], v145 offset:2048
	ds_read_b128 v[210:213], v145 offset:3072
	ds_read_b128 v[214:217], v145 offset:4096
	ds_read_b128 v[218:221], v145 offset:5120
	ds_read_b128 v[222:225], v145 offset:6144
	ds_read_b128 v[226:229], v145 offset:7168
	global_load_lds_dwordx4 v138, s[20:21]
	s_add_i32 m0, s11, 0xe000
	s_nop 0
	global_load_lds_dwordx4 v140, s[20:21]
	s_waitcnt vmcnt(8)
	s_waitcnt lgkmcnt(0)
	s_barrier
	s_setprio 1
	s_waitcnt lgkmcnt(0)
	v_mfma_f32_16x16x32_bf16 v[126:129], v[146:149], v[198:201], v[126:129]
	v_mfma_f32_16x16x32_bf16 v[122:125], v[154:157], v[198:201], v[122:125]
	v_mfma_f32_16x16x32_bf16 v[118:121], v[146:149], v[206:209], v[118:121]
	v_mfma_f32_16x16x32_bf16 v[114:117], v[154:157], v[206:209], v[114:117]
	v_mfma_f32_16x16x32_bf16 v[102:105], v[146:149], v[214:217], v[102:105]
	v_mfma_f32_16x16x32_bf16 v[98:101], v[154:157], v[214:217], v[98:101]
	v_mfma_f32_16x16x32_bf16 v[86:89], v[146:149], v[222:225], v[86:89]
	v_mfma_f32_16x16x32_bf16 v[82:85], v[154:157], v[222:225], v[82:85]
	v_mfma_f32_16x16x32_bf16 v[126:129], v[150:153], v[202:205], v[126:129]
	v_mfma_f32_16x16x32_bf16 v[122:125], v[158:161], v[202:205], v[122:125]
	v_mfma_f32_16x16x32_bf16 v[118:121], v[150:153], v[210:213], v[118:121]
	v_mfma_f32_16x16x32_bf16 v[114:117], v[158:161], v[210:213], v[114:117]
	v_mfma_f32_16x16x32_bf16 v[102:105], v[150:153], v[218:221], v[102:105]
	v_mfma_f32_16x16x32_bf16 v[98:101], v[158:161], v[218:221], v[98:101]
	v_mfma_f32_16x16x32_bf16 v[86:89], v[150:153], v[226:229], v[86:89]
	v_mfma_f32_16x16x32_bf16 v[82:85], v[158:161], v[226:229], v[82:85]
	s_setprio 0
	s_setprio 1
	v_mfma_f32_16x16x32_bf16 v[110:113], v[176:179], v[198:201], v[110:113]
	v_mfma_f32_16x16x32_bf16 v[106:109], v[190:193], v[198:201], v[106:109]
	v_mfma_f32_16x16x32_bf16 v[94:97], v[176:179], v[206:209], v[94:97]
	v_mfma_f32_16x16x32_bf16 v[90:93], v[190:193], v[206:209], v[90:93]
	v_mfma_f32_16x16x32_bf16 v[78:81], v[176:179], v[214:217], v[78:81]
	v_mfma_f32_16x16x32_bf16 v[74:77], v[190:193], v[214:217], v[74:77]
	v_mfma_f32_16x16x32_bf16 v[70:73], v[176:179], v[222:225], v[70:73]
	v_mfma_f32_16x16x32_bf16 v[66:69], v[190:193], v[222:225], v[66:69]
	v_mfma_f32_16x16x32_bf16 v[110:113], v[180:183], v[202:205], v[110:113]
	v_mfma_f32_16x16x32_bf16 v[106:109], v[194:197], v[202:205], v[106:109]
	v_mfma_f32_16x16x32_bf16 v[94:97], v[180:183], v[210:213], v[94:97]
	v_mfma_f32_16x16x32_bf16 v[90:93], v[194:197], v[210:213], v[90:93]
	v_mfma_f32_16x16x32_bf16 v[78:81], v[180:183], v[218:221], v[78:81]
	v_mfma_f32_16x16x32_bf16 v[74:77], v[194:197], v[218:221], v[74:77]
	v_mfma_f32_16x16x32_bf16 v[70:73], v[180:183], v[226:229], v[70:73]
	v_mfma_f32_16x16x32_bf16 v[66:69], v[194:197], v[226:229], v[66:69]
	s_setprio 0
	s_barrier
	s_add_i32 s72, s72, s40
	v_lshl_add_u64 v[162:163], s[22:23], 0, v[134:135]
	s_mov_b32 m0, s72
	ds_read_b128 v[198:201], v145 offset:16384
	ds_read_b128 v[202:205], v145 offset:17408
	ds_read_b128 v[206:209], v145 offset:18432
	ds_read_b128 v[210:213], v145 offset:19456
	ds_read_b128 v[214:217], v145 offset:20480
	ds_read_b128 v[218:221], v145 offset:21504
	ds_read_b128 v[222:225], v145 offset:22528
	ds_read_b128 v[226:229], v145 offset:23552
	global_load_lds_dwordx4 v[162:163], off
	s_add_i32 m0, s72, 0x2000
	s_add_u32 s72, s22, 0x40000
	v_lshl_add_u64 v[230:231], s[22:23], 0, v[130:131]
	s_addc_u32 s73, s23, 0
	s_add_i32 s74, s74, s40
	global_load_lds_dwordx4 v[230:231], off
	s_mov_b32 m0, s74
	v_lshl_add_u64 v[238:239], s[38:39], 0, v[132:133]
	global_load_lds_dwordx4 v134, s[72:73]
	s_add_i32 m0, s74, 0x2000
	s_nop 0
	global_load_lds_dwordx4 v130, s[72:73]
	v_lshl_add_u64 v[236:237], s[38:39], 0, v[136:137]
	s_mov_b32 m0, s11
	s_nop 0
	global_load_lds_dwordx4 v[236:237], off
	s_mov_b32 m0, s41
	s_nop 0
	global_load_lds_dwordx4 v[238:239], off
	s_waitcnt vmcnt(8)
	s_waitcnt lgkmcnt(0)
	s_barrier
; #define PG8_STAGE(bufoff, gbase, voff) do { _Pragma("unroll") for (int _i = 0; _i < 2; ++_i) \
;         __builtin_amdgcn_global_load_lds((const unsigned*)((const char*)(gbase) + (voff)[_i]), (LAS unsigned*)(lds + (bufoff) + ldsw + _i * 8192), 16, 0, 0); } while (0)
; #define PG8_LDA(dst, b, h) do { _Pragma("unroll") for (int m = 0; m < 4; ++m) _Pragma("unroll") for (int k = 0; k < 2; ++k) dst[m][k] = *(const LAS bf16x8*)(lds + PG8_SA(b, h) + aoff + m * 2048 + k * 1024); } while (0)
; #define PG8_LDB(dst, b, h) do { _Pragma("unroll") for (int n = 0; n < 2; ++n) _Pragma("unroll") for (int k = 0; k < 2; ++k) dst[n][k] = *(const LAS bf16x8*)(lds + PG8_SB(b, h) + boff + n * 2048 + k * 1024); } while (0)
; #define PG8_MMA(ai, bj, At, Bt) do { __builtin_amdgcn_s_setprio(1); _Pragma("unroll") for (int m = 0; m < 4; ++m) _Pragma("unroll") for (int n = 0; n < 2; ++n) _Pragma("unroll") for (int k = 0; k < 2; ++k) \
;         acc[ai][bj][m][n] = __builtin_amdgcn_mfma_f32_16x16x32_bf16(Bt[n][k], At[m][k], acc[ai][bj][m][n], 0, 0, 0); __builtin_amdgcn_s_setprio(0); } while (0)
; #define PG8_WAIT_V(n) asm volatile("s_waitcnt vmcnt(" #n ")" ::: "memory")
; #define PG8_WAIT_L(n) asm volatile("s_waitcnt lgkmcnt(" #n ")" ::: "memory")
; #define PG8_BAR __builtin_amdgcn_s_barrier()
; #define PG8_SCHED __builtin_amdgcn_sched_barrier(0)
; template <class Epi>
; DI void gemm_phase(int wid0, LAS unsigned char* lds, const Gemm g, const StaticOrder& S, const Epi& E) {
;     ...
;             PG8_WAIT_V(8); PG8_WAIT_L(0); PG8_BAR; PG8_MMA(1, 0, At, B0); PG8_MMA(1, 1, At, B1); PG8_BAR; PG8_SCHED;
;             PG8_LDB(B0, 1, 0); PG8_LDB(B1, 1, 1); PG8_SCHED; PG8_LDA(At, 1, 0); PG8_STAGE(PG8_SA(0, 1), a2 + hstep, voffA);
;             PG8_WAIT_V(8); PG8_WAIT_L(0); PG8_BAR; PG8_MMA(0, 0, At, B0); PG8_MMA(0, 1, At, B1); PG8_BAR; PG8_SCHED;
	s_setprio 1
	s_waitcnt lgkmcnt(0)
	v_mfma_f32_16x16x32_bf16 v[62:65], v[146:149], v[198:201], v[62:65]
	v_mfma_f32_16x16x32_bf16 v[58:61], v[154:157], v[198:201], v[58:61]
	v_mfma_f32_16x16x32_bf16 v[54:57], v[146:149], v[206:209], v[54:57]
	v_mfma_f32_16x16x32_bf16 v[50:53], v[154:157], v[206:209], v[50:53]
	v_mfma_f32_16x16x32_bf16 v[38:41], v[146:149], v[214:217], v[38:41]
	v_mfma_f32_16x16x32_bf16 v[34:37], v[154:157], v[214:217], v[34:37]
	v_mfma_f32_16x16x32_bf16 v[22:25], v[146:149], v[222:225], v[22:25]
	v_mfma_f32_16x16x32_bf16 v[18:21], v[154:157], v[222:225], v[18:21]
	v_mfma_f32_16x16x32_bf16 v[62:65], v[150:153], v[202:205], v[62:65]
	v_mfma_f32_16x16x32_bf16 v[58:61], v[158:161], v[202:205], v[58:61]
	v_mfma_f32_16x16x32_bf16 v[54:57], v[150:153], v[210:213], v[54:57]
	v_mfma_f32_16x16x32_bf16 v[50:53], v[158:161], v[210:213], v[50:53]
	v_mfma_f32_16x16x32_bf16 v[38:41], v[150:153], v[218:221], v[38:41]
	v_mfma_f32_16x16x32_bf16 v[34:37], v[158:161], v[218:221], v[34:37]
	v_mfma_f32_16x16x32_bf16 v[22:25], v[150:153], v[226:229], v[22:25]
	v_mfma_f32_16x16x32_bf16 v[18:21], v[158:161], v[226:229], v[18:21]
	s_setprio 0
	s_setprio 1
	v_mfma_f32_16x16x32_bf16 v[46:49], v[176:179], v[198:201], v[46:49]
	v_mfma_f32_16x16x32_bf16 v[42:45], v[190:193], v[198:201], v[42:45]
	v_mfma_f32_16x16x32_bf16 v[30:33], v[176:179], v[206:209], v[30:33]
	v_mfma_f32_16x16x32_bf16 v[26:29], v[190:193], v[206:209], v[26:29]
	v_mfma_f32_16x16x32_bf16 v[14:17], v[176:179], v[214:217], v[14:17]
	v_mfma_f32_16x16x32_bf16 v[10:13], v[190:193], v[214:217], v[10:13]
	v_mfma_f32_16x16x32_bf16 v[6:9], v[176:179], v[222:225], v[6:9]
	v_mfma_f32_16x16x32_bf16 v[2:5], v[190:193], v[222:225], v[2:5]
	v_mfma_f32_16x16x32_bf16 v[46:49], v[180:183], v[202:205], v[46:49]
	v_mfma_f32_16x16x32_bf16 v[42:45], v[194:197], v[202:205], v[42:45]
	v_mfma_f32_16x16x32_bf16 v[30:33], v[180:183], v[210:213], v[30:33]
	v_mfma_f32_16x16x32_bf16 v[26:29], v[194:197], v[210:213], v[26:29]
	v_mfma_f32_16x16x32_bf16 v[14:17], v[180:183], v[218:221], v[14:17]
	v_mfma_f32_16x16x32_bf16 v[10:13], v[194:197], v[218:221], v[10:13]
	v_mfma_f32_16x16x32_bf16 v[6:9], v[180:183], v[226:229], v[6:9]
	v_mfma_f32_16x16x32_bf16 v[2:5], v[194:197], v[226:229], v[2:5]
	s_setprio 0
	s_barrier
	s_add_i32 s72, 0, 0x18000
	v_add_u32_e32 v0, s72, v143
	s_add_i32 s73, 0, 0x1c000
	ds_read_b128 v[146:149], v0
	ds_read_b128 v[150:153], v0 offset:1024
	ds_read_b128 v[154:157], v0 offset:2048
	ds_read_b128 v[158:161], v0 offset:3072
	v_add_u32_e32 v0, s73, v143
	ds_read_b128 v[176:179], v0
	ds_read_b128 v[180:183], v0 offset:1024
	ds_read_b128 v[190:193], v0 offset:2048
	ds_read_b128 v[194:197], v0 offset:3072
	s_add_u32 s38, s38, 0x40000
	s_addc_u32 s39, s39, 0
	s_mov_b32 m0, s46
	ds_read_b128 v[198:201], v145 offset:32768
	ds_read_b128 v[202:205], v145 offset:33792
	ds_read_b128 v[206:209], v145 offset:34816
	ds_read_b128 v[210:213], v145 offset:35840
	ds_read_b128 v[214:217], v145 offset:36864
	ds_read_b128 v[218:221], v145 offset:37888
	ds_read_b128 v[222:225], v145 offset:38912
	ds_read_b128 v[226:229], v145 offset:39936
	global_load_lds_dwordx4 v136, s[38:39]
	v_lshl_add_u64 v[240:241], s[38:39], 0, v[132:133]
	s_mov_b32 m0, s47
	s_nop 0
	global_load_lds_dwordx4 v[240:241], off
	s_waitcnt vmcnt(8)
	s_waitcnt lgkmcnt(0)
	s_barrier
	s_setprio 1
	s_waitcnt lgkmcnt(0)
	v_mfma_f32_16x16x32_bf16 v[126:129], v[146:149], v[198:201], v[126:129]
	v_mfma_f32_16x16x32_bf16 v[122:125], v[154:157], v[198:201], v[122:125]
	v_mfma_f32_16x16x32_bf16 v[118:121], v[146:149], v[206:209], v[118:121]
	v_mfma_f32_16x16x32_bf16 v[114:117], v[154:157], v[206:209], v[114:117]
	v_mfma_f32_16x16x32_bf16 v[102:105], v[146:149], v[214:217], v[102:105]
	v_mfma_f32_16x16x32_bf16 v[98:101], v[154:157], v[214:217], v[98:101]
	v_mfma_f32_16x16x32_bf16 v[86:89], v[146:149], v[222:225], v[86:89]
	v_mfma_f32_16x16x32_bf16 v[82:85], v[154:157], v[222:225], v[82:85]
	v_mfma_f32_16x16x32_bf16 v[126:129], v[150:153], v[202:205], v[126:129]
	v_mfma_f32_16x16x32_bf16 v[122:125], v[158:161], v[202:205], v[122:125]
	v_mfma_f32_16x16x32_bf16 v[118:121], v[150:153], v[210:213], v[118:121]
	v_mfma_f32_16x16x32_bf16 v[114:117], v[158:161], v[210:213], v[114:117]
	v_mfma_f32_16x16x32_bf16 v[102:105], v[150:153], v[218:221], v[102:105]
	v_mfma_f32_16x16x32_bf16 v[98:101], v[158:161], v[218:221], v[98:101]
	v_mfma_f32_16x16x32_bf16 v[86:89], v[150:153], v[226:229], v[86:89]
	v_mfma_f32_16x16x32_bf16 v[82:85], v[158:161], v[226:229], v[82:85]
	s_setprio 0
	s_setprio 1
	v_mfma_f32_16x16x32_bf16 v[110:113], v[176:179], v[198:201], v[110:113]
	v_mfma_f32_16x16x32_bf16 v[106:109], v[190:193], v[198:201], v[106:109]
	v_mfma_f32_16x16x32_bf16 v[94:97], v[176:179], v[206:209], v[94:97]
	v_mfma_f32_16x16x32_bf16 v[90:93], v[190:193], v[206:209], v[90:93]
	v_mfma_f32_16x16x32_bf16 v[78:81], v[176:179], v[214:217], v[78:81]
	v_mfma_f32_16x16x32_bf16 v[74:77], v[190:193], v[214:217], v[74:77]
	v_mfma_f32_16x16x32_bf16 v[70:73], v[176:179], v[222:225], v[70:73]
	v_mfma_f32_16x16x32_bf16 v[66:69], v[190:193], v[222:225], v[66:69]
	v_mfma_f32_16x16x32_bf16 v[110:113], v[180:183], v[202:205], v[110:113]
	v_mfma_f32_16x16x32_bf16 v[106:109], v[194:197], v[202:205], v[106:109]
	v_mfma_f32_16x16x32_bf16 v[94:97], v[180:183], v[210:213], v[94:97]
	v_mfma_f32_16x16x32_bf16 v[90:93], v[194:197], v[210:213], v[90:93]
	v_mfma_f32_16x16x32_bf16 v[78:81], v[180:183], v[218:221], v[78:81]
	v_mfma_f32_16x16x32_bf16 v[74:77], v[194:197], v[218:221], v[74:77]
	v_mfma_f32_16x16x32_bf16 v[70:73], v[180:183], v[226:229], v[70:73]
	v_mfma_f32_16x16x32_bf16 v[66:69], v[194:197], v[226:229], v[66:69]
	s_setprio 0
	s_barrier
; #define PG8_STAGE(bufoff, gbase, voff) do { _Pragma("unroll") for (int _i = 0; _i < 2; ++_i) \
;         __builtin_amdgcn_global_load_lds((const unsigned*)((const char*)(gbase) + (voff)[_i]), (LAS unsigned*)(lds + (bufoff) + ldsw + _i * 8192), 16, 0, 0); } while (0)
; #define PG8_LDA(dst, b, h) do { _Pragma("unroll") for (int m = 0; m < 4; ++m) _Pragma("unroll") for (int k = 0; k < 2; ++k) dst[m][k] = *(const LAS bf16x8*)(lds + PG8_SA(b, h) + aoff + m * 2048 + k * 1024); } while (0)
; #define PG8_MMA(ai, bj, At, Bt) do { __builtin_amdgcn_s_setprio(1); _Pragma("unroll") for (int m = 0; m < 4; ++m) _Pragma("unroll") for (int n = 0; n < 2; ++n) _Pragma("unroll") for (int k = 0; k < 2; ++k) \
;         acc[ai][bj][m][n] = __builtin_amdgcn_mfma_f32_16x16x32_bf16(Bt[n][k], At[m][k], acc[ai][bj][m][n], 0, 0, 0); __builtin_amdgcn_s_setprio(0); } while (0)
; #define PG8_WAIT_V(n) asm volatile("s_waitcnt vmcnt(" #n ")" ::: "memory")
; #define PG8_WAIT_L(n) asm volatile("s_waitcnt lgkmcnt(" #n ")" ::: "memory")
; #define PG8_BAR __builtin_amdgcn_s_barrier()
; #define PG8_SCHED __builtin_amdgcn_sched_barrier(0)
; template <class Epi>
; DI void gemm_phase(int wid0, LAS unsigned char* lds, const Gemm g, const StaticOrder& S, const Epi& E) {
;     ...
;         for (int t = 0; t < nt; t += 2) {
;             const bool last = (t == nt - 2);
;             const char* a1 = cA + (size_t)(t + 1) * kstep;
;             const char* a2 = last ? nA : cA + (size_t)(t + 2) * kstep; const char* b2 = last ? nB : cB + (size_t)(t + 2) * kstep;
;     ...
;             PG8_LDA(At, 1, 1); PG8_STAGE(PG8_SB(1, 0), b3, voffB); PG8_STAGE(PG8_SB(1, 1), b3 + hstep, voffB); PG8_STAGE(PG8_SA(1, 0), a3, voffA);
;             PG8_WAIT_V(8); PG8_WAIT_L(0); PG8_BAR; PG8_MMA(1, 0, At, B0); PG8_MMA(1, 1, At, B1); PG8_BAR; PG8_SCHED;
;         }
	s_add_i32 s38, s72, s40
	v_lshl_add_u64 v[162:163], v[162:163], 0, s[30:31]
	s_mov_b32 m0, s38
	ds_read_b128 v[198:201], v145 offset:49152
	ds_read_b128 v[202:205], v145 offset:50176
	ds_read_b128 v[206:209], v145 offset:51200
	ds_read_b128 v[210:213], v145 offset:52224
	ds_read_b128 v[214:217], v145 offset:53248
	ds_read_b128 v[218:221], v145 offset:54272
	ds_read_b128 v[222:225], v145 offset:55296
	ds_read_b128 v[226:229], v145 offset:56320
	global_load_lds_dwordx4 v[162:163], off
	s_add_i32 m0, s38, 0x2000
	s_add_u32 s22, s22, 0x40080
	v_lshl_add_u64 v[162:163], v[230:231], 0, s[30:31]
	s_addc_u32 s23, s23, 0
	s_add_i32 s38, s73, s40
	global_load_lds_dwordx4 v[162:163], off
	s_mov_b32 m0, s38
	s_nop 0
	global_load_lds_dwordx4 v134, s[22:23]
	s_add_i32 m0, s38, 0x2000
	s_nop 0
	global_load_lds_dwordx4 v130, s[22:23]
	v_lshl_add_u64 v[162:163], v[236:237], 0, s[30:31]
	s_mov_b32 m0, s2
	s_nop 0
	global_load_lds_dwordx4 v[162:163], off
	v_lshl_add_u64 v[162:163], v[238:239], 0, s[30:31]
	s_mov_b32 m0, s48
	s_nop 0
	global_load_lds_dwordx4 v[162:163], off
	s_waitcnt vmcnt(8)
	s_waitcnt lgkmcnt(0)
	s_barrier
	s_setprio 1
	s_waitcnt lgkmcnt(0)
	v_mfma_f32_16x16x32_bf16 v[62:65], v[146:149], v[198:201], v[62:65]
	v_mfma_f32_16x16x32_bf16 v[58:61], v[154:157], v[198:201], v[58:61]
	v_mfma_f32_16x16x32_bf16 v[54:57], v[146:149], v[206:209], v[54:57]
	v_mfma_f32_16x16x32_bf16 v[50:53], v[154:157], v[206:209], v[50:53]
	v_mfma_f32_16x16x32_bf16 v[38:41], v[146:149], v[214:217], v[38:41]
	v_mfma_f32_16x16x32_bf16 v[34:37], v[154:157], v[214:217], v[34:37]
	v_mfma_f32_16x16x32_bf16 v[22:25], v[146:149], v[222:225], v[22:25]
	v_mfma_f32_16x16x32_bf16 v[18:21], v[154:157], v[222:225], v[18:21]
	v_mfma_f32_16x16x32_bf16 v[62:65], v[150:153], v[202:205], v[62:65]
	v_mfma_f32_16x16x32_bf16 v[58:61], v[158:161], v[202:205], v[58:61]
	v_mfma_f32_16x16x32_bf16 v[54:57], v[150:153], v[210:213], v[54:57]
	v_mfma_f32_16x16x32_bf16 v[50:53], v[158:161], v[210:213], v[50:53]
	v_mfma_f32_16x16x32_bf16 v[38:41], v[150:153], v[218:221], v[38:41]
	v_mfma_f32_16x16x32_bf16 v[34:37], v[158:161], v[218:221], v[34:37]
	v_mfma_f32_16x16x32_bf16 v[22:25], v[150:153], v[226:229], v[22:25]
	v_mfma_f32_16x16x32_bf16 v[18:21], v[158:161], v[226:229], v[18:21]
	s_setprio 0
	s_setprio 1
	v_mfma_f32_16x16x32_bf16 v[46:49], v[176:179], v[198:201], v[46:49]
	v_mfma_f32_16x16x32_bf16 v[42:45], v[190:193], v[198:201], v[42:45]
	v_mfma_f32_16x16x32_bf16 v[30:33], v[176:179], v[206:209], v[30:33]
	v_mfma_f32_16x16x32_bf16 v[26:29], v[190:193], v[206:209], v[26:29]
	v_mfma_f32_16x16x32_bf16 v[14:17], v[176:179], v[214:217], v[14:17]
	v_mfma_f32_16x16x32_bf16 v[10:13], v[190:193], v[214:217], v[10:13]
	v_mfma_f32_16x16x32_bf16 v[6:9], v[176:179], v[222:225], v[6:9]
	v_mfma_f32_16x16x32_bf16 v[2:5], v[190:193], v[222:225], v[2:5]
	v_mfma_f32_16x16x32_bf16 v[46:49], v[180:183], v[202:205], v[46:49]
	v_mfma_f32_16x16x32_bf16 v[42:45], v[194:197], v[202:205], v[42:45]
	v_mfma_f32_16x16x32_bf16 v[30:33], v[180:183], v[210:213], v[30:33]
	v_mfma_f32_16x16x32_bf16 v[26:29], v[194:197], v[210:213], v[26:29]
	v_mfma_f32_16x16x32_bf16 v[14:17], v[180:183], v[218:221], v[14:17]
	v_mfma_f32_16x16x32_bf16 v[10:13], v[194:197], v[218:221], v[10:13]
	v_mfma_f32_16x16x32_bf16 v[6:9], v[180:183], v[226:229], v[6:9]
	v_mfma_f32_16x16x32_bf16 v[2:5], v[194:197], v[226:229], v[2:5]
	s_setprio 0
	s_barrier
	s_add_i32 s71, s71, 2
	s_add_u32 s20, s20, 0x100
	s_addc_u32 s21, s21, 0
	s_add_u32 s69, s69, 0x100
	s_addc_u32 s70, s70, 0
	s_cmp_gt_u32 s71, 13
	s_cbranch_scc0 .LBB0_139
	s_and_b64 vcc, exec, s[8:9]
	s_cbranch_vccz .LBB0_142
	s_barrier

; #define PG8_STAGE(bufoff, gbase, voff) do { _Pragma("unroll") for (int _i = 0; _i < 2; ++_i) \
;         __builtin_amdgcn_global_load_lds((const unsigned*)((const char*)(gbase) + (voff)[_i]), (LAS unsigned*)(lds + (bufoff) + ldsw + _i * 8192), 16, 0, 0); } while (0)
; #define PG8_LDA(dst, b, h) do { _Pragma("unroll") for (int m = 0; m < 4; ++m) _Pragma("unroll") for (int k = 0; k < 2; ++k) dst[m][k] = *(const LAS bf16x8*)(lds + PG8_SA(b, h) + aoff + m * 2048 + k * 1024); } while (0)
; #define PG8_LDB(dst, b, h) do { _Pragma("unroll") for (int n = 0; n < 2; ++n) _Pragma("unroll") for (int k = 0; k < 2; ++k) dst[n][k] = *(const LAS bf16x8*)(lds + PG8_SB(b, h) + boff + n * 2048 + k * 1024); } while (0)
; #define PG8_MMA(ai, bj, At, Bt) do { __builtin_amdgcn_s_setprio(1); _Pragma("unroll") for (int m = 0; m < 4; ++m) _Pragma("unroll") for (int n = 0; n < 2; ++n) _Pragma("unroll") for (int k = 0; k < 2; ++k) \
;         acc[ai][bj][m][n] = __builtin_amdgcn_mfma_f32_16x16x32_bf16(Bt[n][k], At[m][k], acc[ai][bj][m][n], 0, 0, 0); __builtin_amdgcn_s_setprio(0); } while (0)
; #define PG8_WAIT_V(n) asm volatile("s_waitcnt vmcnt(" #n ")" ::: "memory")
; #define PG8_WAIT_L(n) asm volatile("s_waitcnt lgkmcnt(" #n ")" ::: "memory")
; #define PG8_BAR __builtin_amdgcn_s_barrier()
; #define PG8_SCHED __builtin_amdgcn_sched_barrier(0)
; template <class Epi>
; DI void gemm_phase(int wid0, LAS unsigned char* lds, const Gemm g, const StaticOrder& S, const Epi& E) {
;     ...
;             const char* a1 = cA + (size_t)(t + 1) * kstep;
;             const char* a2 = last ? nA : cA + (size_t)(t + 2) * kstep; const char* b2 = last ? nB : cB + (size_t)(t + 2) * kstep;
;             const char* a3 = a2 + kstep; const char* b3 = b2 + kstep;
;             PG8_LDB(B0, 0, 0); PG8_LDB(B1, 0, 1); PG8_SCHED; PG8_LDA(At, 0, 0); PG8_STAGE(PG8_SA(1, 1), a1 + hstep, voffA);
;             PG8_WAIT_V(8); PG8_WAIT_L(0); PG8_BAR; PG8_MMA(0, 0, At, B0); PG8_MMA(0, 1, At, B1); PG8_BAR; PG8_SCHED;
;             PG8_LDA(At, 0, 1); PG8_STAGE(PG8_SB(0, 0), b2, voffB); PG8_STAGE(PG8_SB(0, 1), b2 + hstep, voffB); PG8_STAGE(PG8_SA(0, 0), a2, voffA);
;             PG8_WAIT_V(8); PG8_WAIT_L(0); PG8_BAR; PG8_MMA(1, 0, At, B0); PG8_MMA(1, 1, At, B1); PG8_BAR; PG8_SCHED;
.LBB0_207:
	s_add_u32 s46, s44, 0xfff80080
	s_addc_u32 s47, s45, -1
	s_add_i32 s72, 0, 0x10000
	s_cmp_eq_u32 s71, 28
	s_cselect_b32 s49, s19, s47
	s_cselect_b32 s48, s66, s46
	v_add_u32_e32 v144, s72, v147
	s_cselect_b32 s47, s17, s70
	s_cselect_b32 s46, s67, s69
	s_add_i32 s74, 0, 0x14000
	ds_read_b128 v[140:143], v144
	ds_read_b128 v[150:153], v144 offset:1024
	ds_read_b128 v[154:157], v144 offset:2048
	ds_read_b128 v[158:161], v144 offset:3072
	v_add_u32_e32 v144, s74, v147
	ds_read_b128 v[176:179], v144
	ds_read_b128 v[180:183], v144 offset:1024
	ds_read_b128 v[190:193], v144 offset:2048
	ds_read_b128 v[194:197], v144 offset:3072
	s_add_i32 m0, s41, 0xc000
	ds_read_b128 v[198:201], v149
	ds_read_b128 v[202:205], v149 offset:1024
	ds_read_b128 v[206:209], v149 offset:2048
	ds_read_b128 v[210:213], v149 offset:3072
	ds_read_b128 v[214:217], v149 offset:4096
	ds_read_b128 v[218:221], v149 offset:5120
	ds_read_b128 v[222:225], v149 offset:6144
	ds_read_b128 v[226:229], v149 offset:7168
	global_load_lds_dwordx4 v136, s[44:45]
	s_add_i32 m0, s41, 0xe000
	s_nop 0
	global_load_lds_dwordx4 v138, s[44:45]
	s_waitcnt vmcnt(8)
	s_waitcnt lgkmcnt(0)
	s_barrier
	s_setprio 1
	s_waitcnt lgkmcnt(0)
	v_mfma_f32_16x16x32_bf16 v[126:129], v[140:143], v[198:201], v[126:129]
	v_mfma_f32_16x16x32_bf16 v[122:125], v[154:157], v[198:201], v[122:125]
	v_mfma_f32_16x16x32_bf16 v[110:113], v[140:143], v[206:209], v[110:113]
	v_mfma_f32_16x16x32_bf16 v[106:109], v[154:157], v[206:209], v[106:109]
	v_mfma_f32_16x16x32_bf16 v[94:97], v[140:143], v[214:217], v[94:97]
	v_mfma_f32_16x16x32_bf16 v[90:93], v[154:157], v[214:217], v[90:93]
	v_mfma_f32_16x16x32_bf16 v[78:81], v[140:143], v[222:225], v[78:81]
	v_mfma_f32_16x16x32_bf16 v[74:77], v[154:157], v[222:225], v[74:77]
	v_mfma_f32_16x16x32_bf16 v[126:129], v[150:153], v[202:205], v[126:129]
	v_mfma_f32_16x16x32_bf16 v[122:125], v[158:161], v[202:205], v[122:125]
	v_mfma_f32_16x16x32_bf16 v[110:113], v[150:153], v[210:213], v[110:113]
	v_mfma_f32_16x16x32_bf16 v[106:109], v[158:161], v[210:213], v[106:109]
	v_mfma_f32_16x16x32_bf16 v[94:97], v[150:153], v[218:221], v[94:97]
	v_mfma_f32_16x16x32_bf16 v[90:93], v[158:161], v[218:221], v[90:93]
	v_mfma_f32_16x16x32_bf16 v[78:81], v[150:153], v[226:229], v[78:81]
	v_mfma_f32_16x16x32_bf16 v[74:77], v[158:161], v[226:229], v[74:77]
	s_setprio 0
	s_setprio 1
	v_mfma_f32_16x16x32_bf16 v[118:121], v[176:179], v[198:201], v[118:121]
	v_mfma_f32_16x16x32_bf16 v[114:117], v[190:193], v[198:201], v[114:117]
	v_mfma_f32_16x16x32_bf16 v[102:105], v[176:179], v[206:209], v[102:105]
	v_mfma_f32_16x16x32_bf16 v[98:101], v[190:193], v[206:209], v[98:101]
	v_mfma_f32_16x16x32_bf16 v[86:89], v[176:179], v[214:217], v[86:89]
	v_mfma_f32_16x16x32_bf16 v[82:85], v[190:193], v[214:217], v[82:85]
	v_mfma_f32_16x16x32_bf16 v[70:73], v[176:179], v[222:225], v[70:73]
	v_mfma_f32_16x16x32_bf16 v[66:69], v[190:193], v[222:225], v[66:69]
	v_mfma_f32_16x16x32_bf16 v[118:121], v[180:183], v[202:205], v[118:121]
	v_mfma_f32_16x16x32_bf16 v[114:117], v[194:197], v[202:205], v[114:117]
	v_mfma_f32_16x16x32_bf16 v[102:105], v[180:183], v[210:213], v[102:105]
	v_mfma_f32_16x16x32_bf16 v[98:101], v[194:197], v[210:213], v[98:101]
	v_mfma_f32_16x16x32_bf16 v[86:89], v[180:183], v[218:221], v[86:89]
	v_mfma_f32_16x16x32_bf16 v[82:85], v[194:197], v[218:221], v[82:85]
	v_mfma_f32_16x16x32_bf16 v[70:73], v[180:183], v[226:229], v[70:73]
	v_mfma_f32_16x16x32_bf16 v[66:69], v[194:197], v[226:229], v[66:69]
	s_setprio 0
	s_barrier
	s_add_i32 s72, s72, s40
	v_lshl_add_u64 v[144:145], s[46:47], 0, v[0:1]
	s_mov_b32 m0, s72
	ds_read_b128 v[198:201], v149 offset:16384
	ds_read_b128 v[202:205], v149 offset:17408
	ds_read_b128 v[206:209], v149 offset:18432
	ds_read_b128 v[210:213], v149 offset:19456
	ds_read_b128 v[214:217], v149 offset:20480
	ds_read_b128 v[218:221], v149 offset:21504
	ds_read_b128 v[222:225], v149 offset:22528
	ds_read_b128 v[226:229], v149 offset:23552
	global_load_lds_dwordx4 v[144:145], off
	s_add_i32 m0, s72, 0x2000
	s_add_u32 s72, s46, 0x80000
	v_lshl_add_u64 v[162:163], s[46:47], 0, v[130:131]
	s_addc_u32 s73, s47, 0
	s_add_i32 s74, s74, s40
	global_load_lds_dwordx4 v[162:163], off
	v_lshl_add_u64 v[230:231], s[72:73], 0, v[0:1]
	s_mov_b32 m0, s74
	v_lshl_add_u64 v[236:237], s[48:49], 0, v[132:133]
	global_load_lds_dwordx4 v[230:231], off
	s_add_i32 m0, s74, 0x2000
	s_nop 0
	global_load_lds_dwordx4 v130, s[72:73]
	v_lshl_add_u64 v[230:231], s[48:49], 0, v[134:135]
	s_mov_b32 m0, s41
	s_nop 0
	global_load_lds_dwordx4 v[230:231], off
	s_mov_b32 m0, s50
	s_nop 0
	global_load_lds_dwordx4 v[236:237], off
	s_waitcnt vmcnt(8)
	s_waitcnt lgkmcnt(0)
	s_barrier
; #define PG8_STAGE(bufoff, gbase, voff) do { _Pragma("unroll") for (int _i = 0; _i < 2; ++_i) \
;         __builtin_amdgcn_global_load_lds((const unsigned*)((const char*)(gbase) + (voff)[_i]), (LAS unsigned*)(lds + (bufoff) + ldsw + _i * 8192), 16, 0, 0); } while (0)
; #define PG8_LDA(dst, b, h) do { _Pragma("unroll") for (int m = 0; m < 4; ++m) _Pragma("unroll") for (int k = 0; k < 2; ++k) dst[m][k] = *(const LAS bf16x8*)(lds + PG8_SA(b, h) + aoff + m * 2048 + k * 1024); } while (0)
; #define PG8_LDB(dst, b, h) do { _Pragma("unroll") for (int n = 0; n < 2; ++n) _Pragma("unroll") for (int k = 0; k < 2; ++k) dst[n][k] = *(const LAS bf16x8*)(lds + PG8_SB(b, h) + boff + n * 2048 + k * 1024); } while (0)
; #define PG8_MMA(ai, bj, At, Bt) do { __builtin_amdgcn_s_setprio(1); _Pragma("unroll") for (int m = 0; m < 4; ++m) _Pragma("unroll") for (int n = 0; n < 2; ++n) _Pragma("unroll") for (int k = 0; k < 2; ++k) \
;         acc[ai][bj][m][n] = __builtin_amdgcn_mfma_f32_16x16x32_bf16(Bt[n][k], At[m][k], acc[ai][bj][m][n], 0, 0, 0); __builtin_amdgcn_s_setprio(0); } while (0)
; #define PG8_WAIT_V(n) asm volatile("s_waitcnt vmcnt(" #n ")" ::: "memory")
; #define PG8_WAIT_L(n) asm volatile("s_waitcnt lgkmcnt(" #n ")" ::: "memory")
; #define PG8_BAR __builtin_amdgcn_s_barrier()
; #define PG8_SCHED __builtin_amdgcn_sched_barrier(0)
; template <class Epi>
; DI void gemm_phase(int wid0, LAS unsigned char* lds, const Gemm g, const StaticOrder& S, const Epi& E) {
;     ...
;             PG8_WAIT_V(8); PG8_WAIT_L(0); PG8_BAR; PG8_MMA(1, 0, At, B0); PG8_MMA(1, 1, At, B1); PG8_BAR; PG8_SCHED;
;             PG8_LDB(B0, 1, 0); PG8_LDB(B1, 1, 1); PG8_SCHED; PG8_LDA(At, 1, 0); PG8_STAGE(PG8_SA(0, 1), a2 + hstep, voffA);
;             PG8_WAIT_V(8); PG8_WAIT_L(0); PG8_BAR; PG8_MMA(0, 0, At, B0); PG8_MMA(0, 1, At, B1); PG8_BAR; PG8_SCHED;
	s_setprio 1
	s_waitcnt lgkmcnt(0)
	v_mfma_f32_16x16x32_bf16 v[62:65], v[140:143], v[198:201], v[62:65]
	v_mfma_f32_16x16x32_bf16 v[58:61], v[154:157], v[198:201], v[58:61]
	v_mfma_f32_16x16x32_bf16 v[46:49], v[140:143], v[206:209], v[46:49]
	v_mfma_f32_16x16x32_bf16 v[42:45], v[154:157], v[206:209], v[42:45]
	v_mfma_f32_16x16x32_bf16 v[30:33], v[140:143], v[214:217], v[30:33]
	v_mfma_f32_16x16x32_bf16 v[26:29], v[154:157], v[214:217], v[26:29]
	v_mfma_f32_16x16x32_bf16 v[14:17], v[140:143], v[222:225], v[14:17]
	v_mfma_f32_16x16x32_bf16 v[10:13], v[154:157], v[222:225], v[10:13]
	v_mfma_f32_16x16x32_bf16 v[62:65], v[150:153], v[202:205], v[62:65]
	v_mfma_f32_16x16x32_bf16 v[58:61], v[158:161], v[202:205], v[58:61]
	v_mfma_f32_16x16x32_bf16 v[46:49], v[150:153], v[210:213], v[46:49]
	v_mfma_f32_16x16x32_bf16 v[42:45], v[158:161], v[210:213], v[42:45]
	v_mfma_f32_16x16x32_bf16 v[30:33], v[150:153], v[218:221], v[30:33]
	v_mfma_f32_16x16x32_bf16 v[26:29], v[158:161], v[218:221], v[26:29]
	v_mfma_f32_16x16x32_bf16 v[14:17], v[150:153], v[226:229], v[14:17]
	v_mfma_f32_16x16x32_bf16 v[10:13], v[158:161], v[226:229], v[10:13]
	s_setprio 0
	s_setprio 1
	v_mfma_f32_16x16x32_bf16 v[54:57], v[176:179], v[198:201], v[54:57]
	v_mfma_f32_16x16x32_bf16 v[50:53], v[190:193], v[198:201], v[50:53]
	v_mfma_f32_16x16x32_bf16 v[38:41], v[176:179], v[206:209], v[38:41]
	v_mfma_f32_16x16x32_bf16 v[34:37], v[190:193], v[206:209], v[34:37]
	v_mfma_f32_16x16x32_bf16 v[22:25], v[176:179], v[214:217], v[22:25]
	v_mfma_f32_16x16x32_bf16 v[18:21], v[190:193], v[214:217], v[18:21]
	v_mfma_f32_16x16x32_bf16 v[6:9], v[176:179], v[222:225], v[6:9]
	v_mfma_f32_16x16x32_bf16 v[2:5], v[190:193], v[222:225], v[2:5]
	v_mfma_f32_16x16x32_bf16 v[54:57], v[180:183], v[202:205], v[54:57]
	v_mfma_f32_16x16x32_bf16 v[50:53], v[194:197], v[202:205], v[50:53]
	v_mfma_f32_16x16x32_bf16 v[38:41], v[180:183], v[210:213], v[38:41]
	v_mfma_f32_16x16x32_bf16 v[34:37], v[194:197], v[210:213], v[34:37]
	v_mfma_f32_16x16x32_bf16 v[22:25], v[180:183], v[218:221], v[22:25]
	v_mfma_f32_16x16x32_bf16 v[18:21], v[194:197], v[218:221], v[18:21]
	v_mfma_f32_16x16x32_bf16 v[6:9], v[180:183], v[226:229], v[6:9]
	v_mfma_f32_16x16x32_bf16 v[2:5], v[194:197], v[226:229], v[2:5]
	s_setprio 0
	s_barrier
	s_add_i32 s72, 0, 0x18000
	s_add_i32 s73, 0, 0x1c000
	v_add_u32_e32 v158, s72, v147
	v_add_u32_e32 v189, s73, v147
	ds_read_b128 v[140:143], v158
	ds_read_b128 v[150:153], v158 offset:1024
	ds_read_b128 v[154:157], v158 offset:2048
	ds_read_b128 v[158:161], v158 offset:3072
	ds_read_b128 v[176:179], v189
	ds_read_b128 v[180:183], v189 offset:1024
	ds_read_b128 v[190:193], v189 offset:2048
	ds_read_b128 v[194:197], v189 offset:3072
	s_add_u32 s48, s48, 0x80000
	s_addc_u32 s49, s49, 0
	s_mov_b32 m0, s51
	ds_read_b128 v[198:201], v149 offset:32768
	ds_read_b128 v[202:205], v149 offset:33792
	ds_read_b128 v[206:209], v149 offset:34816
	ds_read_b128 v[210:213], v149 offset:35840
	ds_read_b128 v[214:217], v149 offset:36864
	ds_read_b128 v[218:221], v149 offset:37888
	ds_read_b128 v[222:225], v149 offset:38912
	ds_read_b128 v[226:229], v149 offset:39936
	global_load_lds_dwordx4 v134, s[48:49]
	v_lshl_add_u64 v[238:239], s[48:49], 0, v[132:133]
	s_mov_b32 m0, s54
	s_nop 0
	global_load_lds_dwordx4 v[238:239], off
	s_waitcnt vmcnt(8)
	s_waitcnt lgkmcnt(0)
	s_barrier
	s_setprio 1
	s_waitcnt lgkmcnt(0)
	v_mfma_f32_16x16x32_bf16 v[126:129], v[140:143], v[198:201], v[126:129]
	v_mfma_f32_16x16x32_bf16 v[122:125], v[154:157], v[198:201], v[122:125]
	v_mfma_f32_16x16x32_bf16 v[110:113], v[140:143], v[206:209], v[110:113]
	v_mfma_f32_16x16x32_bf16 v[106:109], v[154:157], v[206:209], v[106:109]
	v_mfma_f32_16x16x32_bf16 v[94:97], v[140:143], v[214:217], v[94:97]
	v_mfma_f32_16x16x32_bf16 v[90:93], v[154:157], v[214:217], v[90:93]
	v_mfma_f32_16x16x32_bf16 v[78:81], v[140:143], v[222:225], v[78:81]
	v_mfma_f32_16x16x32_bf16 v[74:77], v[154:157], v[222:225], v[74:77]
	v_mfma_f32_16x16x32_bf16 v[126:129], v[150:153], v[202:205], v[126:129]
	v_mfma_f32_16x16x32_bf16 v[122:125], v[158:161], v[202:205], v[122:125]
	v_mfma_f32_16x16x32_bf16 v[110:113], v[150:153], v[210:213], v[110:113]
	v_mfma_f32_16x16x32_bf16 v[106:109], v[158:161], v[210:213], v[106:109]
	v_mfma_f32_16x16x32_bf16 v[94:97], v[150:153], v[218:221], v[94:97]
	v_mfma_f32_16x16x32_bf16 v[90:93], v[158:161], v[218:221], v[90:93]
	v_mfma_f32_16x16x32_bf16 v[78:81], v[150:153], v[226:229], v[78:81]
	v_mfma_f32_16x16x32_bf16 v[74:77], v[158:161], v[226:229], v[74:77]
	s_setprio 0
	s_setprio 1
	v_mfma_f32_16x16x32_bf16 v[118:121], v[176:179], v[198:201], v[118:121]
	v_mfma_f32_16x16x32_bf16 v[114:117], v[190:193], v[198:201], v[114:117]
	v_mfma_f32_16x16x32_bf16 v[102:105], v[176:179], v[206:209], v[102:105]
	v_mfma_f32_16x16x32_bf16 v[98:101], v[190:193], v[206:209], v[98:101]
	v_mfma_f32_16x16x32_bf16 v[86:89], v[176:179], v[214:217], v[86:89]
	v_mfma_f32_16x16x32_bf16 v[82:85], v[190:193], v[214:217], v[82:85]
	v_mfma_f32_16x16x32_bf16 v[70:73], v[176:179], v[222:225], v[70:73]
	v_mfma_f32_16x16x32_bf16 v[66:69], v[190:193], v[222:225], v[66:69]
	v_mfma_f32_16x16x32_bf16 v[118:121], v[180:183], v[202:205], v[118:121]
	v_mfma_f32_16x16x32_bf16 v[114:117], v[194:197], v[202:205], v[114:117]
	v_mfma_f32_16x16x32_bf16 v[102:105], v[180:183], v[210:213], v[102:105]
	v_mfma_f32_16x16x32_bf16 v[98:101], v[194:197], v[210:213], v[98:101]
	v_mfma_f32_16x16x32_bf16 v[86:89], v[180:183], v[218:221], v[86:89]
	v_mfma_f32_16x16x32_bf16 v[82:85], v[194:197], v[218:221], v[82:85]
	v_mfma_f32_16x16x32_bf16 v[70:73], v[180:183], v[226:229], v[70:73]
	v_mfma_f32_16x16x32_bf16 v[66:69], v[194:197], v[226:229], v[66:69]
	s_setprio 0
	s_barrier
; #define PG8_STAGE(bufoff, gbase, voff) do { _Pragma("unroll") for (int _i = 0; _i < 2; ++_i) \
;         __builtin_amdgcn_global_load_lds((const unsigned*)((const char*)(gbase) + (voff)[_i]), (LAS unsigned*)(lds + (bufoff) + ldsw + _i * 8192), 16, 0, 0); } while (0)
; #define PG8_LDA(dst, b, h) do { _Pragma("unroll") for (int m = 0; m < 4; ++m) _Pragma("unroll") for (int k = 0; k < 2; ++k) dst[m][k] = *(const LAS bf16x8*)(lds + PG8_SA(b, h) + aoff + m * 2048 + k * 1024); } while (0)
; #define PG8_MMA(ai, bj, At, Bt) do { __builtin_amdgcn_s_setprio(1); _Pragma("unroll") for (int m = 0; m < 4; ++m) _Pragma("unroll") for (int n = 0; n < 2; ++n) _Pragma("unroll") for (int k = 0; k < 2; ++k) \
;         acc[ai][bj][m][n] = __builtin_amdgcn_mfma_f32_16x16x32_bf16(Bt[n][k], At[m][k], acc[ai][bj][m][n], 0, 0, 0); __builtin_amdgcn_s_setprio(0); } while (0)
; #define PG8_WAIT_V(n) asm volatile("s_waitcnt vmcnt(" #n ")" ::: "memory")
; #define PG8_WAIT_L(n) asm volatile("s_waitcnt lgkmcnt(" #n ")" ::: "memory")
; #define PG8_BAR __builtin_amdgcn_s_barrier()
; #define PG8_SCHED __builtin_amdgcn_sched_barrier(0)
; template <class Epi>
; DI void gemm_phase(int wid0, LAS unsigned char* lds, const Gemm g, const StaticOrder& S, const Epi& E) {
;     ...
;         for (int t = 0; t < nt; t += 2) {
;             const bool last = (t == nt - 2);
;             const char* a1 = cA + (size_t)(t + 1) * kstep;
;             const char* a2 = last ? nA : cA + (size_t)(t + 2) * kstep; const char* b2 = last ? nB : cB + (size_t)(t + 2) * kstep;
;     ...
;             PG8_LDA(At, 1, 1); PG8_STAGE(PG8_SB(1, 0), b3, voffB); PG8_STAGE(PG8_SB(1, 1), b3 + hstep, voffB); PG8_STAGE(PG8_SA(1, 0), a3, voffA);
;             PG8_WAIT_V(8); PG8_WAIT_L(0); PG8_BAR; PG8_MMA(1, 0, At, B0); PG8_MMA(1, 1, At, B1); PG8_BAR; PG8_SCHED;
;         }
	s_add_i32 s48, s72, s40
	v_lshl_add_u64 v[144:145], v[144:145], 0, s[30:31]
	s_mov_b32 m0, s48
	ds_read_b128 v[198:201], v149 offset:49152
	ds_read_b128 v[202:205], v149 offset:50176
	ds_read_b128 v[206:209], v149 offset:51200
	ds_read_b128 v[210:213], v149 offset:52224
	ds_read_b128 v[214:217], v149 offset:53248
	ds_read_b128 v[218:221], v149 offset:54272
	ds_read_b128 v[222:225], v149 offset:55296
	ds_read_b128 v[226:229], v149 offset:56320
	global_load_lds_dwordx4 v[144:145], off
	s_add_i32 m0, s48, 0x2000
	s_add_u32 s46, s46, 0x80080
	v_lshl_add_u64 v[144:145], v[162:163], 0, s[30:31]
	s_addc_u32 s47, s47, 0
	s_add_i32 s48, s73, s40
	global_load_lds_dwordx4 v[144:145], off
	v_lshl_add_u64 v[144:145], s[46:47], 0, v[0:1]
	s_mov_b32 m0, s48
	s_nop 0
	global_load_lds_dwordx4 v[144:145], off
	s_add_i32 m0, s48, 0x2000
	s_nop 0
	global_load_lds_dwordx4 v130, s[46:47]
	v_lshl_add_u64 v[144:145], v[230:231], 0, s[30:31]
	s_mov_b32 m0, s2
	s_nop 0
	global_load_lds_dwordx4 v[144:145], off
	v_lshl_add_u64 v[144:145], v[236:237], 0, s[30:31]
	s_mov_b32 m0, s55
	s_nop 0
	global_load_lds_dwordx4 v[144:145], off
	s_waitcnt vmcnt(8)
	s_waitcnt lgkmcnt(0)
	s_barrier
	s_setprio 1
	s_waitcnt lgkmcnt(0)
	v_mfma_f32_16x16x32_bf16 v[62:65], v[140:143], v[198:201], v[62:65]
	v_mfma_f32_16x16x32_bf16 v[58:61], v[154:157], v[198:201], v[58:61]
	v_mfma_f32_16x16x32_bf16 v[46:49], v[140:143], v[206:209], v[46:49]
	v_mfma_f32_16x16x32_bf16 v[42:45], v[154:157], v[206:209], v[42:45]
	v_mfma_f32_16x16x32_bf16 v[30:33], v[140:143], v[214:217], v[30:33]
	v_mfma_f32_16x16x32_bf16 v[26:29], v[154:157], v[214:217], v[26:29]
	v_mfma_f32_16x16x32_bf16 v[14:17], v[140:143], v[222:225], v[14:17]
	v_mfma_f32_16x16x32_bf16 v[10:13], v[154:157], v[222:225], v[10:13]
	v_mfma_f32_16x16x32_bf16 v[62:65], v[150:153], v[202:205], v[62:65]
	v_mfma_f32_16x16x32_bf16 v[58:61], v[158:161], v[202:205], v[58:61]
	v_mfma_f32_16x16x32_bf16 v[46:49], v[150:153], v[210:213], v[46:49]
	v_mfma_f32_16x16x32_bf16 v[42:45], v[158:161], v[210:213], v[42:45]
	v_mfma_f32_16x16x32_bf16 v[30:33], v[150:153], v[218:221], v[30:33]
	v_mfma_f32_16x16x32_bf16 v[26:29], v[158:161], v[218:221], v[26:29]
	v_mfma_f32_16x16x32_bf16 v[14:17], v[150:153], v[226:229], v[14:17]
	v_mfma_f32_16x16x32_bf16 v[10:13], v[158:161], v[226:229], v[10:13]
	s_setprio 0
	s_setprio 1
	v_mfma_f32_16x16x32_bf16 v[54:57], v[176:179], v[198:201], v[54:57]
	v_mfma_f32_16x16x32_bf16 v[50:53], v[190:193], v[198:201], v[50:53]
	v_mfma_f32_16x16x32_bf16 v[38:41], v[176:179], v[206:209], v[38:41]
	v_mfma_f32_16x16x32_bf16 v[34:37], v[190:193], v[206:209], v[34:37]
	v_mfma_f32_16x16x32_bf16 v[22:25], v[176:179], v[214:217], v[22:25]
	v_mfma_f32_16x16x32_bf16 v[18:21], v[190:193], v[214:217], v[18:21]
	v_mfma_f32_16x16x32_bf16 v[6:9], v[176:179], v[222:225], v[6:9]
	v_mfma_f32_16x16x32_bf16 v[2:5], v[190:193], v[222:225], v[2:5]
	v_mfma_f32_16x16x32_bf16 v[54:57], v[180:183], v[202:205], v[54:57]
	v_mfma_f32_16x16x32_bf16 v[50:53], v[194:197], v[202:205], v[50:53]
	v_mfma_f32_16x16x32_bf16 v[38:41], v[180:183], v[210:213], v[38:41]
	v_mfma_f32_16x16x32_bf16 v[34:37], v[194:197], v[210:213], v[34:37]
	v_mfma_f32_16x16x32_bf16 v[22:25], v[180:183], v[218:221], v[22:25]
	v_mfma_f32_16x16x32_bf16 v[18:21], v[194:197], v[218:221], v[18:21]
	v_mfma_f32_16x16x32_bf16 v[6:9], v[180:183], v[226:229], v[6:9]
	v_mfma_f32_16x16x32_bf16 v[2:5], v[194:197], v[226:229], v[2:5]
	s_setprio 0
	s_barrier
	s_add_i32 s71, s71, 2
	s_add_u32 s44, s44, 0x100
	s_addc_u32 s45, s45, 0
	s_add_u32 s69, s69, 0x100
	s_addc_u32 s70, s70, 0
	s_cmp_gt_u32 s71, 29
	s_cbranch_scc0 .LBB0_207
	s_and_b64 vcc, exec, s[14:15]
	s_cbranch_vccz .LBB0_210
	s_barrier

; #define PG8_STAGE(bufoff, gbase, voff) do { _Pragma("unroll") for (int _i = 0; _i < 2; ++_i) \
;         __builtin_amdgcn_global_load_lds((const unsigned*)((const char*)(gbase) + (voff)[_i]), (LAS unsigned*)(lds + (bufoff) + ldsw + _i * 8192), 16, 0, 0); } while (0)
; #define PG8_WAIT_V(n) asm volatile("s_waitcnt vmcnt(" #n ")" ::: "memory")
; #define PG8_BAR __builtin_amdgcn_s_barrier()
; template <class Epi>
; DI void gemm_phase(int wid0, LAS unsigned char* lds, const Gemm g, const StaticOrder& S, const Epi& E) {
;     ...
;     for (int i = 0; i < 2; ++i) { int R, C; stage_rc(tid * 16 + i * 8192, R, C); const int Rb = (R & ~31) + perm32(R & 31); voffA[i] = (unsigned)(R * K + C) * 2u; voffB[i] = (unsigned)(Rb * K + C) * 2u; }
;     const size_t kstep = (size_t)(BK * 2);
;     const size_t hstep = (size_t)HALF * K * 2;
;     const size_t tstep = 2 * hstep;
;     const unsigned ldsw = (unsigned)wid * 1024u;
;     const int aoff = lds_byte(wr * 64 + fr, fq * 8), boff = lds_byte(wc * 32 + fr, fq * 8);
;     ...
;     Unit cur, nxt; int ui = 0;
;     if (!S.next(0, cur)) return;
;     f32x4 acc[2][2][4][2];
; #pragma unroll
;     for (int a = 0; a < 2; ++a)
; #pragma unroll
;         for (int b = 0; b < 2; ++b)
; #pragma unroll
;             for (int m = 0; m < 4; ++m)
; #pragma unroll
;                 for (int n = 0; n < 2; ++n) acc[a][b][m][n] = (f32x4){0.f, 0.f, 0.f, 0.f};
;     bf16x8 At[4][2], B0[2][2], B1[2][2];
;     const char* cA = (const char*)g.A + (size_t)cur.pm * tstep; const char* cB = (const char*)g.Bt + (size_t)cur.pn * tstep;
;     PG8_STAGE(PG8_SB(0, 0), cB, voffB); PG8_STAGE(PG8_SB(0, 1), cB + hstep, voffB); PG8_STAGE(PG8_SA(0, 0), cA, voffA); PG8_STAGE(PG8_SA(0, 1), cA + hstep, voffA);
;     if (wr == 1) PG8_BAR;
;     PG8_WAIT_V(2); PG8_BAR;
;     PG8_STAGE(PG8_SB(1, 0), cB + kstep, voffB); PG8_STAGE(PG8_SA(1, 0), cA + kstep, voffA); PG8_STAGE(PG8_SB(1, 1), cB + hstep + kstep, voffB);
;     PG8_WAIT_V(6); PG8_BAR;
.LBB0_271:
	v_mov_b32_e32 v133, v1
	v_lshl_add_u64 v[8:9], s[38:39], 0, v[132:133]
	v_mov_b32_e32 v137, v1
	s_lshl_b32 s5, s5, 5
	v_lshl_add_u64 v[10:11], s[38:39], 0, v[136:137]
	v_mov_b32_e32 v131, v1
	s_and_b32 s5, s5, 0x60
	s_add_i32 m0, s44, 0x18000
	v_lshl_add_u64 v[8:9], v[8:9], 0, s[30:31]
	v_lshl_add_u64 v[12:13], s[28:29], 0, v[130:131]
	v_mov_b32_e32 v135, v1
	s_lshl_b32 s7, s4, 13
	s_lshl_b32 s9, s5, 7
	s_waitcnt vmcnt(2)
	s_barrier
	global_load_lds_dwordx4 v[8:9], off
	v_lshl_add_u64 v[8:9], v[10:11], 0, s[30:31]
	s_add_i32 m0, s44, 0x1a000
	s_add_i32 s48, s44, 0x8000
	s_add_i32 s49, s44, 0xa000
	v_lshl_add_u64 v[14:15], s[28:29], 0, v[134:135]
	global_load_lds_dwordx4 v[8:9], off
	v_lshl_add_u64 v[8:9], v[12:13], 0, s[30:31]
	s_mov_b32 m0, s48
	s_add_u32 s14, s38, 0x40080
	global_load_lds_dwordx4 v[8:9], off
	v_lshl_add_u64 v[8:9], v[14:15], 0, s[30:31]
	s_mov_b32 m0, s49
	s_addc_u32 s15, s39, 0
	global_load_lds_dwordx4 v[8:9], off
	s_add_i32 m0, s44, 0x1c000
	s_nop 0
	global_load_lds_dwordx4 v132, s[14:15]
	v_lshl_add_u64 v[8:9], s[14:15], 0, v[136:137]
	s_add_i32 m0, s44, 0x1e000
	s_cmpk_lt_u32 s10, 0x100
	global_load_lds_dwordx4 v[8:9], off
	v_lshrrev_b32_e32 v9, 1, v0
	v_and_b32_e32 v9, 24, v9
	v_and_b32_e32 v8, 15, v0
	v_lshlrev_b32_e32 v10, 1, v9
	v_lshlrev_b32_e32 v0, 2, v0
	v_lshl_or_b32 v152, s4, 6, v8
	v_lshl_or_b32 v8, v8, 6, v10
	v_and_b32_e32 v0, 32, v0
	v_bitop3_b32 v10, v8, s7, v0 bitop3:0xde
	v_bitop3_b32 v153, v8, s9, v0 bitop3:0xde
	v_lshlrev_b32_e32 v0, 14, v2
	v_and_b32_e32 v0, 0xffff8000, v0
	v_lshl_add_u32 v0, v3, 11, v0
	v_and_b32_e32 v2, 1, v2
	v_lshl_or_b32 v0, v2, 6, v0
	v_lshl_add_u32 v138, v4, 1, v0
	v_lshlrev_b32_e32 v0, 14, v5
	v_and_b32_e32 v0, 0xffff8000, v0
	s_waitcnt vmcnt(6)
	v_lshl_add_u32 v0, v6, 11, v0
	v_and_b32_e32 v2, 1, v5
	v_lshl_or_b32 v0, v2, 6, v0
	s_cselect_b64 s[14:15], -1, 0
	v_or_b32_e32 v154, s5, v9
	v_mov_b32_e32 v139, v1
	v_lshl_add_u32 v140, v7, 1, v0
	v_mov_b32_e32 v141, v1
	s_mov_b32 s50, 0
	v_add_u32_e32 v155, 0, v10
	s_barrier
	s_branch .LBB0_274

; #define PG8_STAGE(bufoff, gbase, voff) do { _Pragma("unroll") for (int _i = 0; _i < 2; ++_i) \
;         __builtin_amdgcn_global_load_lds((const unsigned*)((const char*)(gbase) + (voff)[_i]), (LAS unsigned*)(lds + (bufoff) + ldsw + _i * 8192), 16, 0, 0); } while (0)
; #define PG8_LDA(dst, b, h) do { _Pragma("unroll") for (int m = 0; m < 4; ++m) _Pragma("unroll") for (int k = 0; k < 2; ++k) dst[m][k] = *(const LAS bf16x8*)(lds + PG8_SA(b, h) + aoff + m * 2048 + k * 1024); } while (0)
; #define PG8_LDB(dst, b, h) do { _Pragma("unroll") for (int n = 0; n < 2; ++n) _Pragma("unroll") for (int k = 0; k < 2; ++k) dst[n][k] = *(const LAS bf16x8*)(lds + PG8_SB(b, h) + boff + n * 2048 + k * 1024); } while (0)
; #define PG8_MMA(ai, bj, At, Bt) do { __builtin_amdgcn_s_setprio(1); _Pragma("unroll") for (int m = 0; m < 4; ++m) _Pragma("unroll") for (int n = 0; n < 2; ++n) _Pragma("unroll") for (int k = 0; k < 2; ++k) \
;         acc[ai][bj][m][n] = __builtin_amdgcn_mfma_f32_16x16x32_bf16(Bt[n][k], At[m][k], acc[ai][bj][m][n], 0, 0, 0); __builtin_amdgcn_s_setprio(0); } while (0)
; #define PG8_WAIT_V(n) asm volatile("s_waitcnt vmcnt(" #n ")" ::: "memory")
; #define PG8_WAIT_L(n) asm volatile("s_waitcnt lgkmcnt(" #n ")" ::: "memory")
; #define PG8_BAR __builtin_amdgcn_s_barrier()
; #define PG8_SCHED __builtin_amdgcn_sched_barrier(0)
; template <class Epi>
; DI void gemm_phase(int wid0, LAS unsigned char* lds, const Gemm g, const StaticOrder& S, const Epi& E) {
;     ...
;             const char* a1 = cA + (size_t)(t + 1) * kstep;
;             const char* a2 = last ? nA : cA + (size_t)(t + 2) * kstep; const char* b2 = last ? nB : cB + (size_t)(t + 2) * kstep;
;             const char* a3 = a2 + kstep; const char* b3 = b2 + kstep;
;             PG8_LDB(B0, 0, 0); PG8_LDB(B1, 0, 1); PG8_SCHED; PG8_LDA(At, 0, 0); PG8_STAGE(PG8_SA(1, 1), a1 + hstep, voffA);
;             PG8_WAIT_V(8); PG8_WAIT_L(0); PG8_BAR; PG8_MMA(0, 0, At, B0); PG8_MMA(0, 1, At, B1); PG8_BAR; PG8_SCHED;
;             PG8_LDA(At, 0, 1); PG8_STAGE(PG8_SB(0, 0), b2, voffB); PG8_STAGE(PG8_SB(0, 1), b2 + hstep, voffB); PG8_STAGE(PG8_SA(0, 0), a2, voffA);
;             PG8_WAIT_V(8); PG8_WAIT_L(0); PG8_BAR; PG8_MMA(1, 0, At, B0); PG8_MMA(1, 1, At, B1); PG8_BAR; PG8_SCHED;
.LBB0_277:
	s_add_u32 s38, s28, 0xfffc0080
	s_addc_u32 s39, s29, -1
	s_add_i32 s54, 0, 0x10000
	s_cmp_eq_u32 s51, 12
	s_cselect_b32 s41, s7, s39
	s_cselect_b32 s40, s9, s38
	v_add_u32_e32 v0, s54, v153
	s_cselect_b32 s39, s10, s19
	s_cselect_b32 s38, s11, s17
	s_add_i32 s56, 0, 0x14000
	ds_read_b128 v[142:145], v0
	ds_read_b128 v[146:149], v0 offset:1024
	ds_read_b128 v[156:159], v0 offset:2048
	ds_read_b128 v[160:163], v0 offset:3072
	v_add_u32_e32 v0, s56, v153
	ds_read_b128 v[176:179], v0
	ds_read_b128 v[180:183], v0 offset:1024
	ds_read_b128 v[190:193], v0 offset:2048
	ds_read_b128 v[194:197], v0 offset:3072
	s_add_i32 m0, s44, 0xc000
	ds_read_b128 v[198:201], v155
	ds_read_b128 v[202:205], v155 offset:1024
	ds_read_b128 v[206:209], v155 offset:2048
	ds_read_b128 v[210:213], v155 offset:3072
	ds_read_b128 v[214:217], v155 offset:4096
	ds_read_b128 v[218:221], v155 offset:5120
	ds_read_b128 v[222:225], v155 offset:6144
	ds_read_b128 v[226:229], v155 offset:7168
	global_load_lds_dwordx4 v138, s[28:29]
	s_add_i32 m0, s44, 0xe000
	s_nop 0
	global_load_lds_dwordx4 v140, s[28:29]
	s_waitcnt vmcnt(8)
	s_waitcnt lgkmcnt(0)
	s_barrier
	s_setprio 1
	s_waitcnt lgkmcnt(0)
	v_mfma_f32_16x16x32_bf16 v[126:129], v[142:145], v[198:201], v[126:129]
	v_mfma_f32_16x16x32_bf16 v[122:125], v[156:159], v[198:201], v[122:125]
	v_mfma_f32_16x16x32_bf16 v[110:113], v[142:145], v[206:209], v[110:113]
	v_mfma_f32_16x16x32_bf16 v[106:109], v[156:159], v[206:209], v[106:109]
	v_mfma_f32_16x16x32_bf16 v[94:97], v[142:145], v[214:217], v[94:97]
	v_mfma_f32_16x16x32_bf16 v[90:93], v[156:159], v[214:217], v[90:93]
	v_mfma_f32_16x16x32_bf16 v[78:81], v[142:145], v[222:225], v[78:81]
	v_mfma_f32_16x16x32_bf16 v[74:77], v[156:159], v[222:225], v[74:77]
	v_mfma_f32_16x16x32_bf16 v[126:129], v[146:149], v[202:205], v[126:129]
	v_mfma_f32_16x16x32_bf16 v[122:125], v[160:163], v[202:205], v[122:125]
	v_mfma_f32_16x16x32_bf16 v[110:113], v[146:149], v[210:213], v[110:113]
	v_mfma_f32_16x16x32_bf16 v[106:109], v[160:163], v[210:213], v[106:109]
	v_mfma_f32_16x16x32_bf16 v[94:97], v[146:149], v[218:221], v[94:97]
	v_mfma_f32_16x16x32_bf16 v[90:93], v[160:163], v[218:221], v[90:93]
	v_mfma_f32_16x16x32_bf16 v[78:81], v[146:149], v[226:229], v[78:81]
	v_mfma_f32_16x16x32_bf16 v[74:77], v[160:163], v[226:229], v[74:77]
	s_setprio 0
	s_setprio 1
	v_mfma_f32_16x16x32_bf16 v[118:121], v[176:179], v[198:201], v[118:121]
	v_mfma_f32_16x16x32_bf16 v[114:117], v[190:193], v[198:201], v[114:117]
	v_mfma_f32_16x16x32_bf16 v[102:105], v[176:179], v[206:209], v[102:105]
	v_mfma_f32_16x16x32_bf16 v[98:101], v[190:193], v[206:209], v[98:101]
	v_mfma_f32_16x16x32_bf16 v[86:89], v[176:179], v[214:217], v[86:89]
	v_mfma_f32_16x16x32_bf16 v[82:85], v[190:193], v[214:217], v[82:85]
	v_mfma_f32_16x16x32_bf16 v[70:73], v[176:179], v[222:225], v[70:73]
	v_mfma_f32_16x16x32_bf16 v[66:69], v[190:193], v[222:225], v[66:69]
	v_mfma_f32_16x16x32_bf16 v[118:121], v[180:183], v[202:205], v[118:121]
	v_mfma_f32_16x16x32_bf16 v[114:117], v[194:197], v[202:205], v[114:117]
	v_mfma_f32_16x16x32_bf16 v[102:105], v[180:183], v[210:213], v[102:105]
	v_mfma_f32_16x16x32_bf16 v[98:101], v[194:197], v[210:213], v[98:101]
	v_mfma_f32_16x16x32_bf16 v[86:89], v[180:183], v[218:221], v[86:89]
	v_mfma_f32_16x16x32_bf16 v[82:85], v[194:197], v[218:221], v[82:85]
	v_mfma_f32_16x16x32_bf16 v[70:73], v[180:183], v[226:229], v[70:73]
	v_mfma_f32_16x16x32_bf16 v[66:69], v[194:197], v[226:229], v[66:69]
	s_setprio 0
	s_barrier
	s_add_i32 s54, s54, s2
	v_lshl_add_u64 v[150:151], s[38:39], 0, v[132:133]
	s_mov_b32 m0, s54
	ds_read_b128 v[198:201], v155 offset:16384
	ds_read_b128 v[202:205], v155 offset:17408
	ds_read_b128 v[206:209], v155 offset:18432
	ds_read_b128 v[210:213], v155 offset:19456
	ds_read_b128 v[214:217], v155 offset:20480
	ds_read_b128 v[218:221], v155 offset:21504
	ds_read_b128 v[222:225], v155 offset:22528
	ds_read_b128 v[226:229], v155 offset:23552
	global_load_lds_dwordx4 v[150:151], off
	s_add_i32 m0, s54, 0x2000
	s_add_u32 s54, s38, 0x40000
	v_lshl_add_u64 v[230:231], s[38:39], 0, v[136:137]
	s_addc_u32 s55, s39, 0
	s_add_i32 s56, s56, s2
	global_load_lds_dwordx4 v[230:231], off
	s_mov_b32 m0, s56
	v_lshl_add_u64 v[238:239], s[40:41], 0, v[134:135]
	global_load_lds_dwordx4 v132, s[54:55]
	s_add_i32 m0, s56, 0x2000
	s_nop 0
	global_load_lds_dwordx4 v136, s[54:55]
	v_lshl_add_u64 v[236:237], s[40:41], 0, v[130:131]
	s_mov_b32 m0, s44
	s_nop 0
	global_load_lds_dwordx4 v[236:237], off
	s_mov_b32 m0, s45
	s_nop 0
	global_load_lds_dwordx4 v[238:239], off
	s_waitcnt vmcnt(8)
	s_waitcnt lgkmcnt(0)
	s_barrier
; #define PG8_STAGE(bufoff, gbase, voff) do { _Pragma("unroll") for (int _i = 0; _i < 2; ++_i) \
;         __builtin_amdgcn_global_load_lds((const unsigned*)((const char*)(gbase) + (voff)[_i]), (LAS unsigned*)(lds + (bufoff) + ldsw + _i * 8192), 16, 0, 0); } while (0)
; #define PG8_LDA(dst, b, h) do { _Pragma("unroll") for (int m = 0; m < 4; ++m) _Pragma("unroll") for (int k = 0; k < 2; ++k) dst[m][k] = *(const LAS bf16x8*)(lds + PG8_SA(b, h) + aoff + m * 2048 + k * 1024); } while (0)
; #define PG8_LDB(dst, b, h) do { _Pragma("unroll") for (int n = 0; n < 2; ++n) _Pragma("unroll") for (int k = 0; k < 2; ++k) dst[n][k] = *(const LAS bf16x8*)(lds + PG8_SB(b, h) + boff + n * 2048 + k * 1024); } while (0)
; #define PG8_MMA(ai, bj, At, Bt) do { __builtin_amdgcn_s_setprio(1); _Pragma("unroll") for (int m = 0; m < 4; ++m) _Pragma("unroll") for (int n = 0; n < 2; ++n) _Pragma("unroll") for (int k = 0; k < 2; ++k) \
;         acc[ai][bj][m][n] = __builtin_amdgcn_mfma_f32_16x16x32_bf16(Bt[n][k], At[m][k], acc[ai][bj][m][n], 0, 0, 0); __builtin_amdgcn_s_setprio(0); } while (0)
; #define PG8_WAIT_V(n) asm volatile("s_waitcnt vmcnt(" #n ")" ::: "memory")
; #define PG8_WAIT_L(n) asm volatile("s_waitcnt lgkmcnt(" #n ")" ::: "memory")
; #define PG8_BAR __builtin_amdgcn_s_barrier()
; #define PG8_SCHED __builtin_amdgcn_sched_barrier(0)
; template <class Epi>
; DI void gemm_phase(int wid0, LAS unsigned char* lds, const Gemm g, const StaticOrder& S, const Epi& E) {
;     ...
;             PG8_WAIT_V(8); PG8_WAIT_L(0); PG8_BAR; PG8_MMA(1, 0, At, B0); PG8_MMA(1, 1, At, B1); PG8_BAR; PG8_SCHED;
;             PG8_LDB(B0, 1, 0); PG8_LDB(B1, 1, 1); PG8_SCHED; PG8_LDA(At, 1, 0); PG8_STAGE(PG8_SA(0, 1), a2 + hstep, voffA);
;             PG8_WAIT_V(8); PG8_WAIT_L(0); PG8_BAR; PG8_MMA(0, 0, At, B0); PG8_MMA(0, 1, At, B1); PG8_BAR; PG8_SCHED;
	s_setprio 1
	s_waitcnt lgkmcnt(0)
	v_mfma_f32_16x16x32_bf16 v[62:65], v[142:145], v[198:201], v[62:65]
	v_mfma_f32_16x16x32_bf16 v[58:61], v[156:159], v[198:201], v[58:61]
	v_mfma_f32_16x16x32_bf16 v[46:49], v[142:145], v[206:209], v[46:49]
	v_mfma_f32_16x16x32_bf16 v[42:45], v[156:159], v[206:209], v[42:45]
	v_mfma_f32_16x16x32_bf16 v[30:33], v[142:145], v[214:217], v[30:33]
	v_mfma_f32_16x16x32_bf16 v[26:29], v[156:159], v[214:217], v[26:29]
	v_mfma_f32_16x16x32_bf16 v[14:17], v[142:145], v[222:225], v[14:17]
	v_mfma_f32_16x16x32_bf16 v[10:13], v[156:159], v[222:225], v[10:13]
	v_mfma_f32_16x16x32_bf16 v[62:65], v[146:149], v[202:205], v[62:65]
	v_mfma_f32_16x16x32_bf16 v[58:61], v[160:163], v[202:205], v[58:61]
	v_mfma_f32_16x16x32_bf16 v[46:49], v[146:149], v[210:213], v[46:49]
	v_mfma_f32_16x16x32_bf16 v[42:45], v[160:163], v[210:213], v[42:45]
	v_mfma_f32_16x16x32_bf16 v[30:33], v[146:149], v[218:221], v[30:33]
	v_mfma_f32_16x16x32_bf16 v[26:29], v[160:163], v[218:221], v[26:29]
	v_mfma_f32_16x16x32_bf16 v[14:17], v[146:149], v[226:229], v[14:17]
	v_mfma_f32_16x16x32_bf16 v[10:13], v[160:163], v[226:229], v[10:13]
	s_setprio 0
	s_setprio 1
	v_mfma_f32_16x16x32_bf16 v[54:57], v[176:179], v[198:201], v[54:57]
	v_mfma_f32_16x16x32_bf16 v[50:53], v[190:193], v[198:201], v[50:53]
	v_mfma_f32_16x16x32_bf16 v[38:41], v[176:179], v[206:209], v[38:41]
	v_mfma_f32_16x16x32_bf16 v[34:37], v[190:193], v[206:209], v[34:37]
	v_mfma_f32_16x16x32_bf16 v[22:25], v[176:179], v[214:217], v[22:25]
	v_mfma_f32_16x16x32_bf16 v[18:21], v[190:193], v[214:217], v[18:21]
	v_mfma_f32_16x16x32_bf16 v[6:9], v[176:179], v[222:225], v[6:9]
	v_mfma_f32_16x16x32_bf16 v[2:5], v[190:193], v[222:225], v[2:5]
	v_mfma_f32_16x16x32_bf16 v[54:57], v[180:183], v[202:205], v[54:57]
	v_mfma_f32_16x16x32_bf16 v[50:53], v[194:197], v[202:205], v[50:53]
	v_mfma_f32_16x16x32_bf16 v[38:41], v[180:183], v[210:213], v[38:41]
	v_mfma_f32_16x16x32_bf16 v[34:37], v[194:197], v[210:213], v[34:37]
	v_mfma_f32_16x16x32_bf16 v[22:25], v[180:183], v[218:221], v[22:25]
	v_mfma_f32_16x16x32_bf16 v[18:21], v[194:197], v[218:221], v[18:21]
	v_mfma_f32_16x16x32_bf16 v[6:9], v[180:183], v[226:229], v[6:9]
	v_mfma_f32_16x16x32_bf16 v[2:5], v[194:197], v[226:229], v[2:5]
	s_setprio 0
	s_barrier
	s_add_i32 s54, 0, 0x18000
	v_add_u32_e32 v0, s54, v153
	s_add_i32 s55, 0, 0x1c000
	ds_read_b128 v[142:145], v0
	ds_read_b128 v[146:149], v0 offset:1024
	ds_read_b128 v[156:159], v0 offset:2048
	ds_read_b128 v[160:163], v0 offset:3072
	v_add_u32_e32 v0, s55, v153
	ds_read_b128 v[176:179], v0
	ds_read_b128 v[180:183], v0 offset:1024
	ds_read_b128 v[190:193], v0 offset:2048
	ds_read_b128 v[194:197], v0 offset:3072
	s_add_u32 s40, s40, 0x40000
	s_addc_u32 s41, s41, 0
	s_mov_b32 m0, s46
	ds_read_b128 v[198:201], v155 offset:32768
	ds_read_b128 v[202:205], v155 offset:33792
	ds_read_b128 v[206:209], v155 offset:34816
	ds_read_b128 v[210:213], v155 offset:35840
	ds_read_b128 v[214:217], v155 offset:36864
	ds_read_b128 v[218:221], v155 offset:37888
	ds_read_b128 v[222:225], v155 offset:38912
	ds_read_b128 v[226:229], v155 offset:39936
	global_load_lds_dwordx4 v130, s[40:41]
	v_lshl_add_u64 v[240:241], s[40:41], 0, v[134:135]
	s_mov_b32 m0, s47
	s_nop 0
	global_load_lds_dwordx4 v[240:241], off
	s_waitcnt vmcnt(8)
	s_waitcnt lgkmcnt(0)
	s_barrier
	s_setprio 1
	s_waitcnt lgkmcnt(0)
	v_mfma_f32_16x16x32_bf16 v[126:129], v[142:145], v[198:201], v[126:129]
	v_mfma_f32_16x16x32_bf16 v[122:125], v[156:159], v[198:201], v[122:125]
	v_mfma_f32_16x16x32_bf16 v[110:113], v[142:145], v[206:209], v[110:113]
	v_mfma_f32_16x16x32_bf16 v[106:109], v[156:159], v[206:209], v[106:109]
	v_mfma_f32_16x16x32_bf16 v[94:97], v[142:145], v[214:217], v[94:97]
	v_mfma_f32_16x16x32_bf16 v[90:93], v[156:159], v[214:217], v[90:93]
	v_mfma_f32_16x16x32_bf16 v[78:81], v[142:145], v[222:225], v[78:81]
	v_mfma_f32_16x16x32_bf16 v[74:77], v[156:159], v[222:225], v[74:77]
	v_mfma_f32_16x16x32_bf16 v[126:129], v[146:149], v[202:205], v[126:129]
	v_mfma_f32_16x16x32_bf16 v[122:125], v[160:163], v[202:205], v[122:125]
	v_mfma_f32_16x16x32_bf16 v[110:113], v[146:149], v[210:213], v[110:113]
	v_mfma_f32_16x16x32_bf16 v[106:109], v[160:163], v[210:213], v[106:109]
	v_mfma_f32_16x16x32_bf16 v[94:97], v[146:149], v[218:221], v[94:97]
	v_mfma_f32_16x16x32_bf16 v[90:93], v[160:163], v[218:221], v[90:93]
	v_mfma_f32_16x16x32_bf16 v[78:81], v[146:149], v[226:229], v[78:81]
	v_mfma_f32_16x16x32_bf16 v[74:77], v[160:163], v[226:229], v[74:77]
	s_setprio 0
	s_setprio 1
	v_mfma_f32_16x16x32_bf16 v[118:121], v[176:179], v[198:201], v[118:121]
	v_mfma_f32_16x16x32_bf16 v[114:117], v[190:193], v[198:201], v[114:117]
	v_mfma_f32_16x16x32_bf16 v[102:105], v[176:179], v[206:209], v[102:105]
	v_mfma_f32_16x16x32_bf16 v[98:101], v[190:193], v[206:209], v[98:101]
	v_mfma_f32_16x16x32_bf16 v[86:89], v[176:179], v[214:217], v[86:89]
	v_mfma_f32_16x16x32_bf16 v[82:85], v[190:193], v[214:217], v[82:85]
	v_mfma_f32_16x16x32_bf16 v[70:73], v[176:179], v[222:225], v[70:73]
	v_mfma_f32_16x16x32_bf16 v[66:69], v[190:193], v[222:225], v[66:69]
	v_mfma_f32_16x16x32_bf16 v[118:121], v[180:183], v[202:205], v[118:121]
	v_mfma_f32_16x16x32_bf16 v[114:117], v[194:197], v[202:205], v[114:117]
	v_mfma_f32_16x16x32_bf16 v[102:105], v[180:183], v[210:213], v[102:105]
	v_mfma_f32_16x16x32_bf16 v[98:101], v[194:197], v[210:213], v[98:101]
	v_mfma_f32_16x16x32_bf16 v[86:89], v[180:183], v[218:221], v[86:89]
	v_mfma_f32_16x16x32_bf16 v[82:85], v[194:197], v[218:221], v[82:85]
	v_mfma_f32_16x16x32_bf16 v[70:73], v[180:183], v[226:229], v[70:73]
	v_mfma_f32_16x16x32_bf16 v[66:69], v[194:197], v[226:229], v[66:69]
	s_setprio 0
	s_barrier
; #define PG8_STAGE(bufoff, gbase, voff) do { _Pragma("unroll") for (int _i = 0; _i < 2; ++_i) \
;         __builtin_amdgcn_global_load_lds((const unsigned*)((const char*)(gbase) + (voff)[_i]), (LAS unsigned*)(lds + (bufoff) + ldsw + _i * 8192), 16, 0, 0); } while (0)
; #define PG8_LDA(dst, b, h) do { _Pragma("unroll") for (int m = 0; m < 4; ++m) _Pragma("unroll") for (int k = 0; k < 2; ++k) dst[m][k] = *(const LAS bf16x8*)(lds + PG8_SA(b, h) + aoff + m * 2048 + k * 1024); } while (0)
; #define PG8_MMA(ai, bj, At, Bt) do { __builtin_amdgcn_s_setprio(1); _Pragma("unroll") for (int m = 0; m < 4; ++m) _Pragma("unroll") for (int n = 0; n < 2; ++n) _Pragma("unroll") for (int k = 0; k < 2; ++k) \
;         acc[ai][bj][m][n] = __builtin_amdgcn_mfma_f32_16x16x32_bf16(Bt[n][k], At[m][k], acc[ai][bj][m][n], 0, 0, 0); __builtin_amdgcn_s_setprio(0); } while (0)
; #define PG8_WAIT_V(n) asm volatile("s_waitcnt vmcnt(" #n ")" ::: "memory")
; #define PG8_WAIT_L(n) asm volatile("s_waitcnt lgkmcnt(" #n ")" ::: "memory")
; #define PG8_BAR __builtin_amdgcn_s_barrier()
; #define PG8_SCHED __builtin_amdgcn_sched_barrier(0)
; template <class Epi>
; DI void gemm_phase(int wid0, LAS unsigned char* lds, const Gemm g, const StaticOrder& S, const Epi& E) {
;     ...
;         for (int t = 0; t < nt; t += 2) {
;             const bool last = (t == nt - 2);
;             const char* a1 = cA + (size_t)(t + 1) * kstep;
;             const char* a2 = last ? nA : cA + (size_t)(t + 2) * kstep; const char* b2 = last ? nB : cB + (size_t)(t + 2) * kstep;
;     ...
;             PG8_LDA(At, 1, 1); PG8_STAGE(PG8_SB(1, 0), b3, voffB); PG8_STAGE(PG8_SB(1, 1), b3 + hstep, voffB); PG8_STAGE(PG8_SA(1, 0), a3, voffA);
;             PG8_WAIT_V(8); PG8_WAIT_L(0); PG8_BAR; PG8_MMA(1, 0, At, B0); PG8_MMA(1, 1, At, B1); PG8_BAR; PG8_SCHED;
;         }
	s_add_i32 s40, s54, s2
	v_lshl_add_u64 v[150:151], v[150:151], 0, s[30:31]
	s_mov_b32 m0, s40
	ds_read_b128 v[198:201], v155 offset:49152
	ds_read_b128 v[202:205], v155 offset:50176
	ds_read_b128 v[206:209], v155 offset:51200
	ds_read_b128 v[210:213], v155 offset:52224
	ds_read_b128 v[214:217], v155 offset:53248
	ds_read_b128 v[218:221], v155 offset:54272
	ds_read_b128 v[222:225], v155 offset:55296
	ds_read_b128 v[226:229], v155 offset:56320
	global_load_lds_dwordx4 v[150:151], off
	s_add_i32 m0, s40, 0x2000
	s_add_u32 s38, s38, 0x40080
	v_lshl_add_u64 v[150:151], v[230:231], 0, s[30:31]
	s_addc_u32 s39, s39, 0
	s_add_i32 s40, s55, s2
	global_load_lds_dwordx4 v[150:151], off
	s_mov_b32 m0, s40
	s_nop 0
	global_load_lds_dwordx4 v132, s[38:39]
	s_add_i32 m0, s40, 0x2000
	s_nop 0
	global_load_lds_dwordx4 v136, s[38:39]
	v_lshl_add_u64 v[150:151], v[236:237], 0, s[30:31]
	s_mov_b32 m0, s48
	s_nop 0
	global_load_lds_dwordx4 v[150:151], off
	v_lshl_add_u64 v[150:151], v[238:239], 0, s[30:31]
	s_mov_b32 m0, s49
	s_nop 0
	global_load_lds_dwordx4 v[150:151], off
	s_waitcnt vmcnt(8)
	s_waitcnt lgkmcnt(0)
	s_barrier
	s_setprio 1
	s_waitcnt lgkmcnt(0)
	v_mfma_f32_16x16x32_bf16 v[62:65], v[142:145], v[198:201], v[62:65]
	v_mfma_f32_16x16x32_bf16 v[58:61], v[156:159], v[198:201], v[58:61]
	v_mfma_f32_16x16x32_bf16 v[46:49], v[142:145], v[206:209], v[46:49]
	v_mfma_f32_16x16x32_bf16 v[42:45], v[156:159], v[206:209], v[42:45]
	v_mfma_f32_16x16x32_bf16 v[30:33], v[142:145], v[214:217], v[30:33]
	v_mfma_f32_16x16x32_bf16 v[26:29], v[156:159], v[214:217], v[26:29]
	v_mfma_f32_16x16x32_bf16 v[14:17], v[142:145], v[222:225], v[14:17]
	v_mfma_f32_16x16x32_bf16 v[10:13], v[156:159], v[222:225], v[10:13]
	v_mfma_f32_16x16x32_bf16 v[62:65], v[146:149], v[202:205], v[62:65]
	v_mfma_f32_16x16x32_bf16 v[58:61], v[160:163], v[202:205], v[58:61]
	v_mfma_f32_16x16x32_bf16 v[46:49], v[146:149], v[210:213], v[46:49]
	v_mfma_f32_16x16x32_bf16 v[42:45], v[160:163], v[210:213], v[42:45]
	v_mfma_f32_16x16x32_bf16 v[30:33], v[146:149], v[218:221], v[30:33]
	v_mfma_f32_16x16x32_bf16 v[26:29], v[160:163], v[218:221], v[26:29]
	v_mfma_f32_16x16x32_bf16 v[14:17], v[146:149], v[226:229], v[14:17]
	v_mfma_f32_16x16x32_bf16 v[10:13], v[160:163], v[226:229], v[10:13]
	s_setprio 0
	s_setprio 1
	v_mfma_f32_16x16x32_bf16 v[54:57], v[176:179], v[198:201], v[54:57]
	v_mfma_f32_16x16x32_bf16 v[50:53], v[190:193], v[198:201], v[50:53]
	v_mfma_f32_16x16x32_bf16 v[38:41], v[176:179], v[206:209], v[38:41]
	v_mfma_f32_16x16x32_bf16 v[34:37], v[190:193], v[206:209], v[34:37]
	v_mfma_f32_16x16x32_bf16 v[22:25], v[176:179], v[214:217], v[22:25]
	v_mfma_f32_16x16x32_bf16 v[18:21], v[190:193], v[214:217], v[18:21]
	v_mfma_f32_16x16x32_bf16 v[6:9], v[176:179], v[222:225], v[6:9]
	v_mfma_f32_16x16x32_bf16 v[2:5], v[190:193], v[222:225], v[2:5]
	v_mfma_f32_16x16x32_bf16 v[54:57], v[180:183], v[202:205], v[54:57]
	v_mfma_f32_16x16x32_bf16 v[50:53], v[194:197], v[202:205], v[50:53]
	v_mfma_f32_16x16x32_bf16 v[38:41], v[180:183], v[210:213], v[38:41]
	v_mfma_f32_16x16x32_bf16 v[34:37], v[194:197], v[210:213], v[34:37]
	v_mfma_f32_16x16x32_bf16 v[22:25], v[180:183], v[218:221], v[22:25]
	v_mfma_f32_16x16x32_bf16 v[18:21], v[194:197], v[218:221], v[18:21]
	v_mfma_f32_16x16x32_bf16 v[6:9], v[180:183], v[226:229], v[6:9]
	v_mfma_f32_16x16x32_bf16 v[2:5], v[194:197], v[226:229], v[2:5]
	s_setprio 0
	s_barrier
	s_add_i32 s51, s51, 2
	s_add_u32 s28, s28, 0x100
	s_addc_u32 s29, s29, 0
	s_add_u32 s17, s17, 0x100
	s_addc_u32 s19, s19, 0
	s_cmp_gt_u32 s51, 13
	s_cbranch_scc0 .LBB0_277
	s_and_b64 vcc, exec, s[14:15]
	s_cbranch_vccz .LBB0_280
	s_barrier
